# v21 + Hyena hyconv16 stages 2/3: the rows' cache lines touched two barriers earlier (start of the preceding FFT's last Stockham step)
# baseline (speedup 1.0000x reference)
.LBB0_438:
	s_or_b64 exec, exec, s[0:1]
	v_mov_b32_e32 v47, v32
	s_waitcnt lgkmcnt(0)
	s_barrier
	s_mov_b32 s11, s14
	v_and_b32_e32 v81, 31, v47
	v_cvt_f32_ubyte0_e32 v24, v81
	v_mul_f32_e32 v110, 0x3b000000, v24
	v_sin_f32_e32 v24, v110
	v_ashrrev_i32_e32 v0, 4, v47
	v_lshlrev_b32_e32 v0, 3, v0
	v_lshlrev_b32_e32 v1, 3, v47
	v_cos_f32_e32 v110, v110
	v_add3_u32 v25, 0, v0, v1
	ds_read_b64 v[0:1], v25
	ds_read_b64 v[2:3], v25 offset:4352
	ds_read_b64 v[4:5], v25 offset:8704
	ds_read_b64 v[6:7], v25 offset:13056
	ds_read_b64 v[8:9], v25 offset:17408
	ds_read_b64 v[10:11], v25 offset:21760
	ds_read_b64 v[12:13], v25 offset:26112
	ds_read_b64 v[14:15], v25 offset:30464
	ds_read_b64 v[16:17], v25 offset:34816
	ds_read_b64 v[18:19], v25 offset:39168
	ds_read_b64 v[20:21], v25 offset:43520
	ds_read_b64 v[22:23], v25 offset:47872
	v_xor_b32_e32 v111, 0x80000000, v24
	s_waitcnt lgkmcnt(10)
	v_pk_mul_f32 v[118:119], v[2:3], v[24:25] op_sel:[1,0] op_sel_hi:[0,0] neg_hi:[0,1]
	v_pk_fma_f32 v[2:3], v[2:3], v[110:111], v[118:119] op_sel_hi:[1,0,1]
	v_pk_mul_f32 v[118:119], v[24:25], v[110:111] op_sel:[0,1] op_sel_hi:[0,0] neg_hi:[1,0]
	v_pk_fma_f32 v[118:119], v[110:111], v[110:111], v[118:119] op_sel_hi:[0,1,1]
	ds_read_b64 v[26:27], v25 offset:52224
	ds_read_b64 v[28:29], v25 offset:56576
	ds_read_b64 v[30:31], v25 offset:60928
	ds_read_b64 v[102:103], v25 offset:65280
	s_waitcnt lgkmcnt(13)
	v_pk_mul_f32 v[120:121], v[4:5], v[118:119] op_sel:[1,1] op_sel_hi:[0,1] neg_lo:[0,1]
	v_pk_fma_f32 v[4:5], v[4:5], v[118:119], v[120:121] op_sel_hi:[1,0,1]
	v_pk_mul_f32 v[120:121], v[24:25], v[118:119] op_sel:[0,1] op_sel_hi:[0,0] neg_hi:[1,0]
	v_pk_fma_f32 v[118:119], v[110:111], v[118:119], v[120:121] op_sel_hi:[0,1,1]
	s_mov_b32 s35, s30
	s_waitcnt lgkmcnt(12)
	v_pk_mul_f32 v[120:121], v[6:7], v[118:119] op_sel:[1,1] op_sel_hi:[0,1] neg_lo:[0,1]
	v_pk_fma_f32 v[6:7], v[6:7], v[118:119], v[120:121] op_sel_hi:[1,0,1]
	v_pk_mul_f32 v[120:121], v[24:25], v[118:119] op_sel:[0,1] op_sel_hi:[0,0] neg_hi:[1,0]
	v_pk_fma_f32 v[118:119], v[110:111], v[118:119], v[120:121] op_sel_hi:[0,1,1]
	s_mov_b32 s0, s19
	s_waitcnt lgkmcnt(11)
	v_pk_mul_f32 v[120:121], v[8:9], v[118:119] op_sel:[1,1] op_sel_hi:[0,1] neg_lo:[0,1]
	v_pk_fma_f32 v[8:9], v[8:9], v[118:119], v[120:121] op_sel_hi:[1,0,1]
	v_pk_mul_f32 v[120:121], v[24:25], v[118:119] op_sel:[0,1] op_sel_hi:[0,0] neg_hi:[1,0]
	v_pk_fma_f32 v[118:119], v[110:111], v[118:119], v[120:121] op_sel_hi:[0,1,1]
	s_waitcnt lgkmcnt(0)
	v_pk_mul_f32 v[120:121], v[10:11], v[118:119] op_sel:[1,1] op_sel_hi:[0,1] neg_lo:[0,1]
	v_pk_fma_f32 v[10:11], v[10:11], v[118:119], v[120:121] op_sel_hi:[1,0,1]
	v_pk_mul_f32 v[120:121], v[24:25], v[118:119] op_sel:[0,1] op_sel_hi:[0,0] neg_hi:[1,0]
	v_pk_fma_f32 v[118:119], v[110:111], v[118:119], v[120:121] op_sel_hi:[0,1,1]
	s_barrier
	v_pk_mul_f32 v[120:121], v[12:13], v[118:119] op_sel:[1,1] op_sel_hi:[0,1] neg_lo:[0,1]
	v_pk_fma_f32 v[12:13], v[12:13], v[118:119], v[120:121] op_sel_hi:[1,0,1]
	v_pk_mul_f32 v[120:121], v[24:25], v[118:119] op_sel:[0,1] op_sel_hi:[0,0] neg_hi:[1,0]
	v_pk_fma_f32 v[118:119], v[110:111], v[118:119], v[120:121] op_sel_hi:[0,1,1]
	s_nop 0
	v_pk_mul_f32 v[120:121], v[14:15], v[118:119] op_sel:[1,1] op_sel_hi:[0,1] neg_lo:[0,1]
	v_pk_fma_f32 v[14:15], v[14:15], v[118:119], v[120:121] op_sel_hi:[1,0,1]
	v_pk_mul_f32 v[120:121], v[24:25], v[118:119] op_sel:[0,1] op_sel_hi:[0,0] neg_hi:[1,0]
	v_pk_fma_f32 v[118:119], v[110:111], v[118:119], v[120:121] op_sel_hi:[0,1,1]
	s_nop 0
	v_pk_mul_f32 v[120:121], v[16:17], v[118:119] op_sel:[1,1] op_sel_hi:[0,1] neg_lo:[0,1]
	v_pk_fma_f32 v[16:17], v[16:17], v[118:119], v[120:121] op_sel_hi:[1,0,1]
	v_pk_mul_f32 v[120:121], v[24:25], v[118:119] op_sel:[0,1] op_sel_hi:[0,0] neg_hi:[1,0]
	v_pk_fma_f32 v[118:119], v[110:111], v[118:119], v[120:121] op_sel_hi:[0,1,1]
	s_nop 0
	v_pk_mul_f32 v[120:121], v[18:19], v[118:119] op_sel:[1,1] op_sel_hi:[0,1] neg_lo:[0,1]
	v_pk_fma_f32 v[18:19], v[18:19], v[118:119], v[120:121] op_sel_hi:[1,0,1]
	v_pk_mul_f32 v[120:121], v[24:25], v[118:119] op_sel:[0,1] op_sel_hi:[0,0] neg_hi:[1,0]
	v_pk_fma_f32 v[118:119], v[110:111], v[118:119], v[120:121] op_sel_hi:[0,1,1]
	s_nop 0
	v_pk_mul_f32 v[120:121], v[20:21], v[118:119] op_sel:[1,1] op_sel_hi:[0,1] neg_lo:[0,1]
	v_pk_fma_f32 v[20:21], v[20:21], v[118:119], v[120:121] op_sel_hi:[1,0,1]
	v_pk_mul_f32 v[120:121], v[24:25], v[118:119] op_sel:[0,1] op_sel_hi:[0,0] neg_hi:[1,0]
	v_pk_fma_f32 v[118:119], v[110:111], v[118:119], v[120:121] op_sel_hi:[0,1,1]
	s_nop 0
	v_pk_mul_f32 v[120:121], v[22:23], v[118:119] op_sel:[1,1] op_sel_hi:[0,1] neg_lo:[0,1]
	v_pk_fma_f32 v[22:23], v[22:23], v[118:119], v[120:121] op_sel_hi:[1,0,1]
	v_pk_mul_f32 v[120:121], v[24:25], v[118:119] op_sel:[0,1] op_sel_hi:[0,0] neg_hi:[1,0]
	v_pk_fma_f32 v[118:119], v[110:111], v[118:119], v[120:121] op_sel_hi:[0,1,1]
	s_nop 0
	v_pk_mul_f32 v[120:121], v[26:27], v[118:119] op_sel:[1,1] op_sel_hi:[0,1] neg_lo:[0,1]
	v_pk_fma_f32 v[26:27], v[26:27], v[118:119], v[120:121] op_sel_hi:[1,0,1]
	v_pk_mul_f32 v[120:121], v[24:25], v[118:119] op_sel:[0,1] op_sel_hi:[0,0] neg_hi:[1,0]
	v_pk_fma_f32 v[118:119], v[110:111], v[118:119], v[120:121] op_sel_hi:[0,1,1]
	s_nop 0
	v_pk_mul_f32 v[120:121], v[28:29], v[118:119] op_sel:[1,1] op_sel_hi:[0,1] neg_lo:[0,1]
	v_pk_fma_f32 v[28:29], v[28:29], v[118:119], v[120:121] op_sel_hi:[1,0,1]
	v_pk_mul_f32 v[120:121], v[24:25], v[118:119] op_sel:[0,1] op_sel_hi:[0,0] neg_hi:[1,0]
	v_pk_fma_f32 v[118:119], v[110:111], v[118:119], v[120:121] op_sel_hi:[0,1,1]
	v_pk_mul_f32 v[24:25], v[24:25], v[118:119] op_sel:[0,1] op_sel_hi:[0,0] neg_hi:[1,0]
	v_pk_fma_f32 v[24:25], v[110:111], v[118:119], v[24:25] op_sel_hi:[0,1,1]
	v_pk_mul_f32 v[110:111], v[102:103], v[24:25] op_sel:[1,1] op_sel_hi:[0,1] neg_lo:[0,1]
	v_pk_fma_f32 v[24:25], v[102:103], v[24:25], v[110:111] op_sel_hi:[1,0,1]
	v_pk_add_f32 v[102:103], v[0:1], v[16:17]
	v_pk_add_f32 v[0:1], v[0:1], v[16:17] neg_lo:[0,1] neg_hi:[0,1]
	v_pk_add_f32 v[16:17], v[2:3], v[18:19]
	v_pk_add_f32 v[2:3], v[2:3], v[18:19] neg_lo:[0,1] neg_hi:[0,1]
	v_pk_mul_f32 v[120:121], v[30:31], v[118:119] op_sel:[1,1] op_sel_hi:[0,1] neg_lo:[0,1]
	v_pk_mul_f32 v[18:19], v[2:3], s[18:19]
	v_pk_fma_f32 v[30:31], v[30:31], v[118:119], v[120:121] op_sel_hi:[1,0,1]
	v_pk_fma_f32 v[2:3], v[2:3], s[30:31], v[18:19] op_sel:[0,0,1] op_sel_hi:[1,0,0]
	v_pk_add_f32 v[18:19], v[4:5], v[20:21]
	v_pk_add_f32 v[4:5], v[4:5], v[20:21] neg_lo:[0,1] neg_hi:[0,1]
	s_nop 0
	v_pk_mul_f32 v[20:21], v[4:5], s[10:11]
	s_nop 0
	v_pk_fma_f32 v[4:5], v[4:5], s[14:15], v[20:21] op_sel:[0,0,1] op_sel_hi:[1,0,0]
	v_pk_add_f32 v[20:21], v[6:7], v[22:23]
	v_pk_add_f32 v[6:7], v[6:7], v[22:23] neg_lo:[0,1] neg_hi:[0,1]
	s_nop 0
	v_pk_mul_f32 v[22:23], v[6:7], s[34:35]
	s_nop 0
	v_pk_fma_f32 v[6:7], v[6:7], s[0:1], v[22:23] op_sel:[0,0,1] op_sel_hi:[1,0,0]
	v_pk_add_f32 v[22:23], v[8:9], v[26:27]
	v_pk_add_f32 v[8:9], v[8:9], v[26:27] neg_lo:[0,1] neg_hi:[0,1]
	v_pk_add_f32 v[26:27], v[10:11], v[28:29]
	v_pk_add_f32 v[10:11], v[10:11], v[28:29] neg_lo:[0,1] neg_hi:[0,1]
	s_nop 0
	v_pk_mul_f32 v[28:29], v[10:11], s[34:35]
	s_nop 0
	v_pk_fma_f32 v[10:11], v[10:11], s[0:1], v[28:29] op_sel:[0,0,1] op_sel_hi:[1,0,0] neg_lo:[1,0,0] neg_hi:[1,0,0]
	v_pk_add_f32 v[28:29], v[12:13], v[30:31]
	v_pk_add_f32 v[12:13], v[12:13], v[30:31] neg_lo:[0,1] neg_hi:[0,1]
	s_nop 0
	v_pk_mul_f32 v[30:31], v[12:13], s[10:11]
	s_nop 0
	v_pk_fma_f32 v[12:13], v[12:13], s[14:15], v[30:31] op_sel:[0,0,1] op_sel_hi:[1,0,0] neg_lo:[1,0,0] neg_hi:[1,0,0]
	v_pk_add_f32 v[30:31], v[14:15], v[24:25]
	v_pk_add_f32 v[14:15], v[14:15], v[24:25] neg_lo:[0,1] neg_hi:[0,1]
	s_nop 0
	v_pk_mul_f32 v[24:25], v[14:15], s[18:19]
	s_nop 0
	v_pk_fma_f32 v[14:15], v[14:15], s[30:31], v[24:25] op_sel:[0,0,1] op_sel_hi:[1,0,0] neg_lo:[1,0,0] neg_hi:[1,0,0]
	v_pk_add_f32 v[24:25], v[102:103], v[22:23]
	v_pk_add_f32 v[22:23], v[102:103], v[22:23] neg_lo:[0,1] neg_hi:[0,1]
	v_pk_add_f32 v[102:103], v[16:17], v[26:27]
	v_pk_add_f32 v[16:17], v[16:17], v[26:27] neg_lo:[0,1] neg_hi:[0,1]
	s_nop 0
	v_pk_mul_f32 v[26:27], v[16:17], s[10:11]
	s_nop 0
	v_pk_fma_f32 v[16:17], v[16:17], s[14:15], v[26:27] op_sel:[0,0,1] op_sel_hi:[1,0,0]
	v_pk_add_f32 v[26:27], v[18:19], v[28:29]
	v_pk_add_f32 v[18:19], v[18:19], v[28:29] neg_lo:[0,1] neg_hi:[0,1]
	v_pk_add_f32 v[28:29], v[20:21], v[30:31]
	v_pk_add_f32 v[20:21], v[20:21], v[30:31] neg_lo:[0,1] neg_hi:[0,1]
	s_nop 0
	v_pk_mul_f32 v[30:31], v[20:21], s[10:11]
	s_nop 0
	v_pk_fma_f32 v[20:21], v[20:21], s[14:15], v[30:31] op_sel:[0,0,1] op_sel_hi:[1,0,0] neg_lo:[1,0,0] neg_hi:[1,0,0]
	v_pk_add_f32 v[30:31], v[0:1], v[8:9] op_sel:[0,1] op_sel_hi:[1,0] neg_hi:[0,1]
	v_pk_add_f32 v[0:1], v[0:1], v[8:9] op_sel:[0,1] op_sel_hi:[1,0] neg_lo:[0,1]
	v_pk_add_f32 v[8:9], v[2:3], v[10:11]
	v_pk_add_f32 v[2:3], v[2:3], v[10:11] neg_lo:[0,1] neg_hi:[0,1]
	s_nop 0
	v_pk_mul_f32 v[10:11], v[2:3], s[10:11]
	s_nop 0
	v_pk_fma_f32 v[2:3], v[2:3], s[14:15], v[10:11] op_sel:[0,0,1] op_sel_hi:[1,0,0]
	v_pk_add_f32 v[10:11], v[4:5], v[12:13]
	v_pk_add_f32 v[4:5], v[4:5], v[12:13] neg_lo:[0,1] neg_hi:[0,1]
	v_pk_add_f32 v[12:13], v[6:7], v[14:15]
	v_pk_add_f32 v[6:7], v[6:7], v[14:15] neg_lo:[0,1] neg_hi:[0,1]
	s_nop 0
	v_pk_mul_f32 v[14:15], v[6:7], s[10:11]
	s_nop 0
	v_pk_fma_f32 v[6:7], v[6:7], s[14:15], v[14:15] op_sel:[0,0,1] op_sel_hi:[1,0,0] neg_lo:[1,0,0] neg_hi:[1,0,0]
	v_pk_add_f32 v[14:15], v[24:25], v[26:27]
	v_pk_add_f32 v[24:25], v[24:25], v[26:27] neg_lo:[0,1] neg_hi:[0,1]
	v_pk_add_f32 v[26:27], v[102:103], v[28:29]
	v_pk_add_f32 v[28:29], v[102:103], v[28:29] neg_lo:[0,1] neg_hi:[0,1]
	v_pk_add_f32 v[102:103], v[22:23], v[18:19] op_sel:[0,1] op_sel_hi:[1,0] neg_hi:[0,1]
	v_pk_add_f32 v[18:19], v[22:23], v[18:19] op_sel:[0,1] op_sel_hi:[1,0] neg_lo:[0,1]
	v_pk_add_f32 v[22:23], v[16:17], v[20:21]
	v_pk_add_f32 v[16:17], v[16:17], v[20:21] neg_lo:[0,1] neg_hi:[0,1]
	v_pk_add_f32 v[20:21], v[30:31], v[10:11]
	v_pk_add_f32 v[10:11], v[30:31], v[10:11] neg_lo:[0,1] neg_hi:[0,1]
	v_pk_add_f32 v[30:31], v[8:9], v[12:13]
	v_pk_add_f32 v[8:9], v[8:9], v[12:13] neg_lo:[0,1] neg_hi:[0,1]
	v_pk_add_f32 v[12:13], v[0:1], v[4:5] op_sel:[0,1] op_sel_hi:[1,0] neg_hi:[0,1]
	v_pk_add_f32 v[0:1], v[0:1], v[4:5] op_sel:[0,1] op_sel_hi:[1,0] neg_lo:[0,1]
	v_pk_add_f32 v[4:5], v[2:3], v[6:7]
	v_pk_add_f32 v[2:3], v[2:3], v[6:7] neg_lo:[0,1] neg_hi:[0,1]
	s_nop 0
	v_pk_mul_f32 v[2:3], v[2:3], s[22:23]
	v_pk_add_f32 v[6:7], v[14:15], v[26:27]
	v_pk_add_f32 v[14:15], v[14:15], v[26:27] neg_lo:[0,1] neg_hi:[0,1]
	v_pk_add_f32 v[26:27], v[24:25], v[28:29] op_sel:[0,1] op_sel_hi:[1,0] neg_hi:[0,1]
	v_pk_add_f32 v[24:25], v[24:25], v[28:29] op_sel:[0,1] op_sel_hi:[1,0] neg_lo:[0,1]
	v_pk_add_f32 v[28:29], v[102:103], v[22:23]
	v_pk_add_f32 v[22:23], v[102:103], v[22:23] neg_lo:[0,1] neg_hi:[0,1]
	v_pk_add_f32 v[102:103], v[18:19], v[16:17] op_sel:[0,1] op_sel_hi:[1,0] neg_hi:[0,1]
	v_pk_add_f32 v[16:17], v[18:19], v[16:17] op_sel:[0,1] op_sel_hi:[1,0] neg_lo:[0,1]
	v_pk_add_f32 v[18:19], v[20:21], v[30:31]
	v_pk_add_f32 v[20:21], v[20:21], v[30:31] neg_lo:[0,1] neg_hi:[0,1]
	v_pk_add_f32 v[30:31], v[10:11], v[8:9] op_sel:[0,1] op_sel_hi:[1,0] neg_hi:[0,1]
	v_pk_add_f32 v[8:9], v[10:11], v[8:9] op_sel:[0,1] op_sel_hi:[1,0] neg_lo:[0,1]
	v_pk_add_f32 v[10:11], v[12:13], v[4:5]
	v_pk_add_f32 v[4:5], v[12:13], v[4:5] neg_lo:[0,1] neg_hi:[0,1]
	v_pk_add_f32 v[12:13], v[0:1], v[2:3] op_sel:[0,1] op_sel_hi:[1,0]
	v_pk_add_f32 v[0:1], v[0:1], v[2:3] op_sel:[0,1] op_sel_hi:[1,0] neg_lo:[0,1] neg_hi:[0,1]
	v_lshlrev_b32_e32 v2, 4, v47
	v_and_or_b32 v2, v2, s7, v81
	v_ashrrev_i32_e32 v3, 4, v2
	v_lshlrev_b32_e32 v3, 3, v3
	v_lshlrev_b32_e32 v2, 3, v2
	v_add3_u32 v2, 0, v3, v2
	v_add_u32_e32 v3, 0x800, v2
	v_mov_b32_e32 v47, v32
	ds_write2_b64 v2, v[6:7], v[18:19] offset1:34
	ds_write2_b64 v3, v[14:15], v[20:21] offset0:16 offset1:50
	ds_write2_b64 v2, v[26:27], v[30:31] offset0:136 offset1:170
	ds_write2_b64 v3, v[24:25], v[8:9] offset0:152 offset1:186
	ds_write2_b64 v2, v[28:29], v[10:11] offset0:68 offset1:102
	ds_write2_b64 v3, v[22:23], v[4:5] offset0:84 offset1:118
	ds_write2_b64 v2, v[102:103], v[12:13] offset0:204 offset1:238
	ds_write2_b64 v3, v[16:17], v[0:1] offset0:220 offset1:254
	s_waitcnt lgkmcnt(0)
	s_barrier
	v_lshl_add_u64 v[224:225], v[78:79], 0, v[172:173]
	s_mov_b64 s[100:101], 0x40000
	v_lshl_add_u64 v[228:229], v[224:225], 0, s[100:101]
	global_load_dword v226, v[228:229], off
	s_mov_b64 s[100:101], 0x100000
	v_lshl_add_u64 v[228:229], v[224:225], 0, s[100:101]
	global_load_dword v226, v[228:229], off
	s_nop 0
	v_and_b32_e32 v81, 0x1ff, v47
	v_cvt_f32_u32_e32 v24, v81
	v_ashrrev_i32_e32 v0, 4, v47
	v_lshlrev_b32_e32 v0, 3, v0
	v_lshlrev_b32_e32 v1, 3, v47
	v_mul_f32_e32 v110, 0x39000000, v24
	v_sin_f32_e32 v24, v110
	v_cos_f32_e32 v110, v110
	v_add3_u32 v25, 0, v0, v1
	ds_read_b64 v[0:1], v25
	ds_read_b64 v[2:3], v25 offset:4352
	ds_read_b64 v[4:5], v25 offset:8704
	ds_read_b64 v[6:7], v25 offset:13056
	ds_read_b64 v[8:9], v25 offset:17408
	ds_read_b64 v[10:11], v25 offset:21760
	ds_read_b64 v[12:13], v25 offset:26112
	ds_read_b64 v[14:15], v25 offset:30464
	v_xor_b32_e32 v111, 0x80000000, v24
	s_waitcnt lgkmcnt(6)
	v_pk_mul_f32 v[118:119], v[2:3], v[24:25] op_sel:[1,0] op_sel_hi:[0,0] neg_hi:[0,1]
	v_pk_fma_f32 v[2:3], v[2:3], v[110:111], v[118:119] op_sel_hi:[1,0,1]
	v_pk_mul_f32 v[118:119], v[24:25], v[110:111] op_sel:[0,1] op_sel_hi:[0,0] neg_hi:[1,0]
	v_pk_fma_f32 v[118:119], v[110:111], v[110:111], v[118:119] op_sel_hi:[0,1,1]
	ds_read_b64 v[16:17], v25 offset:34816
	ds_read_b64 v[18:19], v25 offset:39168
	ds_read_b64 v[20:21], v25 offset:43520
	ds_read_b64 v[22:23], v25 offset:47872
	s_waitcnt lgkmcnt(9)
	v_pk_mul_f32 v[120:121], v[4:5], v[118:119] op_sel:[1,1] op_sel_hi:[0,1] neg_lo:[0,1]
	v_pk_fma_f32 v[4:5], v[4:5], v[118:119], v[120:121] op_sel_hi:[1,0,1]
	v_pk_mul_f32 v[120:121], v[24:25], v[118:119] op_sel:[0,1] op_sel_hi:[0,0] neg_hi:[1,0]
	v_pk_fma_f32 v[118:119], v[110:111], v[118:119], v[120:121] op_sel_hi:[0,1,1]
	ds_read_b64 v[26:27], v25 offset:52224
	ds_read_b64 v[28:29], v25 offset:56576
	ds_read_b64 v[30:31], v25 offset:60928
	ds_read_b64 v[102:103], v25 offset:65280
	s_waitcnt lgkmcnt(12)
	v_pk_mul_f32 v[120:121], v[6:7], v[118:119] op_sel:[1,1] op_sel_hi:[0,1] neg_lo:[0,1]
	v_pk_fma_f32 v[6:7], v[6:7], v[118:119], v[120:121] op_sel_hi:[1,0,1]
	v_pk_mul_f32 v[120:121], v[24:25], v[118:119] op_sel:[0,1] op_sel_hi:[0,0] neg_hi:[1,0]
	v_pk_fma_f32 v[118:119], v[110:111], v[118:119], v[120:121] op_sel_hi:[0,1,1]
	s_waitcnt lgkmcnt(0)
	v_pk_mul_f32 v[120:121], v[8:9], v[118:119] op_sel:[1,1] op_sel_hi:[0,1] neg_lo:[0,1]
	v_pk_fma_f32 v[8:9], v[8:9], v[118:119], v[120:121] op_sel_hi:[1,0,1]
	v_pk_mul_f32 v[120:121], v[24:25], v[118:119] op_sel:[0,1] op_sel_hi:[0,0] neg_hi:[1,0]
	v_pk_fma_f32 v[118:119], v[110:111], v[118:119], v[120:121] op_sel_hi:[0,1,1]
	s_barrier
	v_pk_mul_f32 v[120:121], v[10:11], v[118:119] op_sel:[1,1] op_sel_hi:[0,1] neg_lo:[0,1]
	v_pk_fma_f32 v[10:11], v[10:11], v[118:119], v[120:121] op_sel_hi:[1,0,1]
	v_pk_mul_f32 v[120:121], v[24:25], v[118:119] op_sel:[0,1] op_sel_hi:[0,0] neg_hi:[1,0]
	v_pk_fma_f32 v[118:119], v[110:111], v[118:119], v[120:121] op_sel_hi:[0,1,1]
	s_nop 0
	v_pk_mul_f32 v[120:121], v[12:13], v[118:119] op_sel:[1,1] op_sel_hi:[0,1] neg_lo:[0,1]
	v_pk_fma_f32 v[12:13], v[12:13], v[118:119], v[120:121] op_sel_hi:[1,0,1]
	v_pk_mul_f32 v[120:121], v[24:25], v[118:119] op_sel:[0,1] op_sel_hi:[0,0] neg_hi:[1,0]
	v_pk_fma_f32 v[118:119], v[110:111], v[118:119], v[120:121] op_sel_hi:[0,1,1]
	s_nop 0
	v_pk_mul_f32 v[120:121], v[14:15], v[118:119] op_sel:[1,1] op_sel_hi:[0,1] neg_lo:[0,1]
	v_pk_fma_f32 v[14:15], v[14:15], v[118:119], v[120:121] op_sel_hi:[1,0,1]
	v_pk_mul_f32 v[120:121], v[24:25], v[118:119] op_sel:[0,1] op_sel_hi:[0,0] neg_hi:[1,0]
	v_pk_fma_f32 v[118:119], v[110:111], v[118:119], v[120:121] op_sel_hi:[0,1,1]
	s_nop 0
	v_pk_mul_f32 v[120:121], v[16:17], v[118:119] op_sel:[1,1] op_sel_hi:[0,1] neg_lo:[0,1]
	v_pk_fma_f32 v[16:17], v[16:17], v[118:119], v[120:121] op_sel_hi:[1,0,1]
	v_pk_mul_f32 v[120:121], v[24:25], v[118:119] op_sel:[0,1] op_sel_hi:[0,0] neg_hi:[1,0]
	v_pk_fma_f32 v[118:119], v[110:111], v[118:119], v[120:121] op_sel_hi:[0,1,1]
	s_nop 0
	v_pk_mul_f32 v[120:121], v[18:19], v[118:119] op_sel:[1,1] op_sel_hi:[0,1] neg_lo:[0,1]
	v_pk_fma_f32 v[18:19], v[18:19], v[118:119], v[120:121] op_sel_hi:[1,0,1]
	v_pk_mul_f32 v[120:121], v[24:25], v[118:119] op_sel:[0,1] op_sel_hi:[0,0] neg_hi:[1,0]
	v_pk_fma_f32 v[118:119], v[110:111], v[118:119], v[120:121] op_sel_hi:[0,1,1]
	s_nop 0
	v_pk_mul_f32 v[120:121], v[20:21], v[118:119] op_sel:[1,1] op_sel_hi:[0,1] neg_lo:[0,1]
	v_pk_fma_f32 v[20:21], v[20:21], v[118:119], v[120:121] op_sel_hi:[1,0,1]
	v_pk_mul_f32 v[120:121], v[24:25], v[118:119] op_sel:[0,1] op_sel_hi:[0,0] neg_hi:[1,0]
	v_pk_fma_f32 v[118:119], v[110:111], v[118:119], v[120:121] op_sel_hi:[0,1,1]
	s_nop 0
	v_pk_mul_f32 v[120:121], v[22:23], v[118:119] op_sel:[1,1] op_sel_hi:[0,1] neg_lo:[0,1]
	v_pk_fma_f32 v[22:23], v[22:23], v[118:119], v[120:121] op_sel_hi:[1,0,1]
	v_pk_mul_f32 v[120:121], v[24:25], v[118:119] op_sel:[0,1] op_sel_hi:[0,0] neg_hi:[1,0]
	v_pk_fma_f32 v[118:119], v[110:111], v[118:119], v[120:121] op_sel_hi:[0,1,1]
	s_nop 0
	v_pk_mul_f32 v[120:121], v[26:27], v[118:119] op_sel:[1,1] op_sel_hi:[0,1] neg_lo:[0,1]
	v_pk_fma_f32 v[26:27], v[26:27], v[118:119], v[120:121] op_sel_hi:[1,0,1]
	v_pk_mul_f32 v[120:121], v[24:25], v[118:119] op_sel:[0,1] op_sel_hi:[0,0] neg_hi:[1,0]
	v_pk_fma_f32 v[118:119], v[110:111], v[118:119], v[120:121] op_sel_hi:[0,1,1]
	s_nop 0
	v_pk_mul_f32 v[120:121], v[28:29], v[118:119] op_sel:[1,1] op_sel_hi:[0,1] neg_lo:[0,1]
	v_pk_fma_f32 v[28:29], v[28:29], v[118:119], v[120:121] op_sel_hi:[1,0,1]
	v_pk_mul_f32 v[120:121], v[24:25], v[118:119] op_sel:[0,1] op_sel_hi:[0,0] neg_hi:[1,0]
	v_pk_fma_f32 v[118:119], v[110:111], v[118:119], v[120:121] op_sel_hi:[0,1,1]
	v_pk_mul_f32 v[24:25], v[24:25], v[118:119] op_sel:[0,1] op_sel_hi:[0,0] neg_hi:[1,0]
	v_pk_fma_f32 v[24:25], v[110:111], v[118:119], v[24:25] op_sel_hi:[0,1,1]
	v_pk_mul_f32 v[110:111], v[102:103], v[24:25] op_sel:[1,1] op_sel_hi:[0,1] neg_lo:[0,1]
	v_pk_fma_f32 v[24:25], v[102:103], v[24:25], v[110:111] op_sel_hi:[1,0,1]
	v_pk_add_f32 v[102:103], v[0:1], v[16:17]
	v_pk_add_f32 v[0:1], v[0:1], v[16:17] neg_lo:[0,1] neg_hi:[0,1]
	v_pk_add_f32 v[16:17], v[2:3], v[18:19]
	v_pk_add_f32 v[2:3], v[2:3], v[18:19] neg_lo:[0,1] neg_hi:[0,1]
	v_pk_mul_f32 v[120:121], v[30:31], v[118:119] op_sel:[1,1] op_sel_hi:[0,1] neg_lo:[0,1]
	v_pk_mul_f32 v[18:19], v[2:3], s[18:19]
	v_pk_fma_f32 v[30:31], v[30:31], v[118:119], v[120:121] op_sel_hi:[1,0,1]
	v_pk_fma_f32 v[2:3], v[2:3], s[30:31], v[18:19] op_sel:[0,0,1] op_sel_hi:[1,0,0]
	v_pk_add_f32 v[18:19], v[4:5], v[20:21]
	v_pk_add_f32 v[4:5], v[4:5], v[20:21] neg_lo:[0,1] neg_hi:[0,1]
	s_nop 0
	v_pk_mul_f32 v[20:21], v[4:5], s[10:11]
	s_nop 0
	v_pk_fma_f32 v[4:5], v[4:5], s[14:15], v[20:21] op_sel:[0,0,1] op_sel_hi:[1,0,0]
	v_pk_add_f32 v[20:21], v[6:7], v[22:23]
	v_pk_add_f32 v[6:7], v[6:7], v[22:23] neg_lo:[0,1] neg_hi:[0,1]
	s_nop 0
	v_pk_mul_f32 v[22:23], v[6:7], s[34:35]
	s_nop 0
	v_pk_fma_f32 v[6:7], v[6:7], s[0:1], v[22:23] op_sel:[0,0,1] op_sel_hi:[1,0,0]
	v_pk_add_f32 v[22:23], v[8:9], v[26:27]
	v_pk_add_f32 v[8:9], v[8:9], v[26:27] neg_lo:[0,1] neg_hi:[0,1]
	v_pk_add_f32 v[26:27], v[10:11], v[28:29]
	v_pk_add_f32 v[10:11], v[10:11], v[28:29] neg_lo:[0,1] neg_hi:[0,1]
	s_nop 0
	v_pk_mul_f32 v[28:29], v[10:11], s[34:35]
	s_nop 0
	v_pk_fma_f32 v[10:11], v[10:11], s[0:1], v[28:29] op_sel:[0,0,1] op_sel_hi:[1,0,0] neg_lo:[1,0,0] neg_hi:[1,0,0]
	v_pk_add_f32 v[28:29], v[12:13], v[30:31]
	v_pk_add_f32 v[12:13], v[12:13], v[30:31] neg_lo:[0,1] neg_hi:[0,1]
	s_nop 0
	v_pk_mul_f32 v[30:31], v[12:13], s[10:11]
	s_nop 0
	v_pk_fma_f32 v[12:13], v[12:13], s[14:15], v[30:31] op_sel:[0,0,1] op_sel_hi:[1,0,0] neg_lo:[1,0,0] neg_hi:[1,0,0]
	v_pk_add_f32 v[30:31], v[14:15], v[24:25]
	v_pk_add_f32 v[14:15], v[14:15], v[24:25] neg_lo:[0,1] neg_hi:[0,1]
	s_nop 0
	v_pk_mul_f32 v[24:25], v[14:15], s[18:19]
	s_nop 0
	v_pk_fma_f32 v[14:15], v[14:15], s[30:31], v[24:25] op_sel:[0,0,1] op_sel_hi:[1,0,0] neg_lo:[1,0,0] neg_hi:[1,0,0]
	v_pk_add_f32 v[24:25], v[102:103], v[22:23]
	v_pk_add_f32 v[22:23], v[102:103], v[22:23] neg_lo:[0,1] neg_hi:[0,1]
	v_pk_add_f32 v[102:103], v[16:17], v[26:27]
	v_pk_add_f32 v[16:17], v[16:17], v[26:27] neg_lo:[0,1] neg_hi:[0,1]
	s_nop 0
	v_pk_mul_f32 v[26:27], v[16:17], s[10:11]
	s_nop 0
	v_pk_fma_f32 v[16:17], v[16:17], s[14:15], v[26:27] op_sel:[0,0,1] op_sel_hi:[1,0,0]
	v_pk_add_f32 v[26:27], v[18:19], v[28:29]
	v_pk_add_f32 v[18:19], v[18:19], v[28:29] neg_lo:[0,1] neg_hi:[0,1]
	v_pk_add_f32 v[28:29], v[20:21], v[30:31]
	v_pk_add_f32 v[20:21], v[20:21], v[30:31] neg_lo:[0,1] neg_hi:[0,1]
	s_nop 0
	v_pk_mul_f32 v[30:31], v[20:21], s[10:11]
	s_nop 0
	v_pk_fma_f32 v[20:21], v[20:21], s[14:15], v[30:31] op_sel:[0,0,1] op_sel_hi:[1,0,0] neg_lo:[1,0,0] neg_hi:[1,0,0]
	v_pk_add_f32 v[30:31], v[0:1], v[8:9] op_sel:[0,1] op_sel_hi:[1,0] neg_hi:[0,1]
	v_pk_add_f32 v[0:1], v[0:1], v[8:9] op_sel:[0,1] op_sel_hi:[1,0] neg_lo:[0,1]
	v_pk_add_f32 v[8:9], v[2:3], v[10:11]
	v_pk_add_f32 v[2:3], v[2:3], v[10:11] neg_lo:[0,1] neg_hi:[0,1]
	s_nop 0
	v_pk_mul_f32 v[10:11], v[2:3], s[10:11]
	s_nop 0
	v_pk_fma_f32 v[2:3], v[2:3], s[14:15], v[10:11] op_sel:[0,0,1] op_sel_hi:[1,0,0]
	v_pk_add_f32 v[10:11], v[4:5], v[12:13]
	v_pk_add_f32 v[4:5], v[4:5], v[12:13] neg_lo:[0,1] neg_hi:[0,1]
	v_pk_add_f32 v[12:13], v[6:7], v[14:15]
	v_pk_add_f32 v[6:7], v[6:7], v[14:15] neg_lo:[0,1] neg_hi:[0,1]
	s_nop 0
	v_pk_mul_f32 v[14:15], v[6:7], s[10:11]
	s_nop 0
	v_pk_fma_f32 v[6:7], v[6:7], s[14:15], v[14:15] op_sel:[0,0,1] op_sel_hi:[1,0,0] neg_lo:[1,0,0] neg_hi:[1,0,0]
	v_pk_add_f32 v[14:15], v[24:25], v[26:27]
	v_pk_add_f32 v[24:25], v[24:25], v[26:27] neg_lo:[0,1] neg_hi:[0,1]
	v_pk_add_f32 v[26:27], v[102:103], v[28:29]
	v_pk_add_f32 v[28:29], v[102:103], v[28:29] neg_lo:[0,1] neg_hi:[0,1]
	v_pk_add_f32 v[102:103], v[22:23], v[18:19] op_sel:[0,1] op_sel_hi:[1,0] neg_hi:[0,1]
	v_pk_add_f32 v[18:19], v[22:23], v[18:19] op_sel:[0,1] op_sel_hi:[1,0] neg_lo:[0,1]
	v_pk_add_f32 v[22:23], v[16:17], v[20:21]
	v_pk_add_f32 v[16:17], v[16:17], v[20:21] neg_lo:[0,1] neg_hi:[0,1]
	v_pk_add_f32 v[20:21], v[30:31], v[10:11]
	v_pk_add_f32 v[10:11], v[30:31], v[10:11] neg_lo:[0,1] neg_hi:[0,1]
	v_pk_add_f32 v[30:31], v[8:9], v[12:13]
	v_pk_add_f32 v[8:9], v[8:9], v[12:13] neg_lo:[0,1] neg_hi:[0,1]
	v_pk_add_f32 v[12:13], v[0:1], v[4:5] op_sel:[0,1] op_sel_hi:[1,0] neg_hi:[0,1]
	v_pk_add_f32 v[0:1], v[0:1], v[4:5] op_sel:[0,1] op_sel_hi:[1,0] neg_lo:[0,1]
	v_pk_add_f32 v[4:5], v[2:3], v[6:7]
	v_pk_add_f32 v[2:3], v[2:3], v[6:7] neg_lo:[0,1] neg_hi:[0,1]
	s_nop 0
	v_pk_mul_f32 v[2:3], v[2:3], s[22:23]
	v_pk_add_f32 v[6:7], v[14:15], v[26:27]
	v_pk_add_f32 v[14:15], v[14:15], v[26:27] neg_lo:[0,1] neg_hi:[0,1]
	v_pk_add_f32 v[26:27], v[24:25], v[28:29] op_sel:[0,1] op_sel_hi:[1,0] neg_hi:[0,1]
	v_pk_add_f32 v[24:25], v[24:25], v[28:29] op_sel:[0,1] op_sel_hi:[1,0] neg_lo:[0,1]
	v_pk_add_f32 v[28:29], v[102:103], v[22:23]
	v_pk_add_f32 v[22:23], v[102:103], v[22:23] neg_lo:[0,1] neg_hi:[0,1]
	v_pk_add_f32 v[102:103], v[18:19], v[16:17] op_sel:[0,1] op_sel_hi:[1,0] neg_hi:[0,1]
	v_pk_add_f32 v[16:17], v[18:19], v[16:17] op_sel:[0,1] op_sel_hi:[1,0] neg_lo:[0,1]
	v_pk_add_f32 v[18:19], v[20:21], v[30:31]
	v_pk_add_f32 v[20:21], v[20:21], v[30:31] neg_lo:[0,1] neg_hi:[0,1]
	v_pk_add_f32 v[30:31], v[10:11], v[8:9] op_sel:[0,1] op_sel_hi:[1,0] neg_hi:[0,1]
	v_pk_add_f32 v[8:9], v[10:11], v[8:9] op_sel:[0,1] op_sel_hi:[1,0] neg_lo:[0,1]
	v_pk_add_f32 v[10:11], v[12:13], v[4:5]
	v_pk_add_f32 v[4:5], v[12:13], v[4:5] neg_lo:[0,1] neg_hi:[0,1]
	v_pk_add_f32 v[12:13], v[0:1], v[2:3] op_sel:[0,1] op_sel_hi:[1,0]
	v_pk_add_f32 v[0:1], v[0:1], v[2:3] op_sel:[0,1] op_sel_hi:[1,0] neg_lo:[0,1] neg_hi:[0,1]
	v_lshlrev_b32_e32 v2, 4, v47
	v_and_or_b32 v2, v2, s15, v81
	v_ashrrev_i32_e32 v3, 4, v2
	v_lshlrev_b32_e32 v3, 3, v3
	v_lshlrev_b32_e32 v2, 3, v2
	v_add3_u32 v2, 0, v3, v2
	ds_write_b64 v2, v[6:7]
	ds_write_b64 v2, v[14:15] offset:34816
	ds_write_b64 v2, v[26:27] offset:17408
	ds_write_b64 v2, v[24:25] offset:52224
	ds_write_b64 v2, v[28:29] offset:8704
	ds_write_b64 v2, v[22:23] offset:43520
	ds_write_b64 v2, v[102:103] offset:26112
	ds_write_b64 v2, v[16:17] offset:60928
	ds_write_b64 v2, v[18:19] offset:4352
	ds_write_b64 v2, v[20:21] offset:39168
	ds_write_b64 v2, v[30:31] offset:21760
	ds_write_b64 v2, v[8:9] offset:56576
	ds_write_b64 v2, v[10:11] offset:13056
	ds_write_b64 v2, v[4:5] offset:47872
	ds_write_b64 v2, v[12:13] offset:30464
	ds_write_b64 v2, v[0:1] offset:65280
	s_waitcnt lgkmcnt(0)
	s_barrier
	s_and_saveexec_b64 s[0:1], s[42:43]
	s_cbranch_execz .LBB0_448
	v_lshl_add_u64 v[2:3], v[78:79], 0, v[172:173]
	s_mov_b64 s[4:5], 0x40000
	v_lshl_add_u64 v[0:1], v[2:3], 0, s[4:5]
	v_add_co_u32_e32 v2, vcc, 0x40000, v2
	v_cmp_ne_u32_e64 s[44:45], 0, v39
	s_nop 0
	v_addc_co_u32_e32 v3, vcc, 0, v3, vcc
	global_load_dwordx4 v[12:15], v[2:3], off
	global_load_dwordx4 v[8:11], v[0:1], off offset:16
	v_mov_b32_e32 v19, 0
	v_mov_b32_e32 v18, 0
	v_mov_b32_e32 v33, 0
	s_and_saveexec_b64 s[4:5], s[44:45]
	s_cbranch_execz .LBB0_441
	global_load_ushort v33, v[0:1], off offset:-2

.LBB0_490:
	s_or_b64 exec, exec, s[0:1]
	v_mov_b32_e32 v37, v32
	s_waitcnt lgkmcnt(0)
	s_barrier
	s_mov_b32 s11, s14
	v_and_b32_e32 v47, 31, v37
	v_cvt_f32_ubyte0_e32 v24, v47
	v_mul_f32_e32 v81, 0x3b000000, v24
	v_sin_f32_e32 v24, v81
	v_ashrrev_i32_e32 v0, 4, v37
	v_lshlrev_b32_e32 v0, 3, v0
	v_lshlrev_b32_e32 v1, 3, v37
	v_cos_f32_e32 v84, v81
	v_add3_u32 v25, 0, v0, v1
	ds_read_b64 v[0:1], v25
	ds_read_b64 v[2:3], v25 offset:4352
	ds_read_b64 v[4:5], v25 offset:8704
	ds_read_b64 v[6:7], v25 offset:13056
	ds_read_b64 v[8:9], v25 offset:17408
	ds_read_b64 v[10:11], v25 offset:21760
	ds_read_b64 v[12:13], v25 offset:26112
	ds_read_b64 v[14:15], v25 offset:30464
	ds_read_b64 v[16:17], v25 offset:34816
	ds_read_b64 v[18:19], v25 offset:39168
	ds_read_b64 v[20:21], v25 offset:43520
	ds_read_b64 v[22:23], v25 offset:47872
	v_xor_b32_e32 v85, 0x80000000, v24
	s_waitcnt lgkmcnt(10)
	v_pk_mul_f32 v[118:119], v[2:3], v[24:25] op_sel:[1,0] op_sel_hi:[0,0] neg_hi:[0,1]
	v_pk_fma_f32 v[2:3], v[2:3], v[84:85], v[118:119] op_sel_hi:[1,0,1]
	v_pk_mul_f32 v[118:119], v[24:25], v[84:85] op_sel:[0,1] op_sel_hi:[0,0] neg_hi:[1,0]
	v_pk_fma_f32 v[118:119], v[84:85], v[84:85], v[118:119] op_sel_hi:[0,1,1]
	ds_read_b64 v[26:27], v25 offset:52224
	ds_read_b64 v[28:29], v25 offset:56576
	ds_read_b64 v[30:31], v25 offset:60928
	ds_read_b64 v[82:83], v25 offset:65280
	s_waitcnt lgkmcnt(13)
	v_pk_mul_f32 v[120:121], v[4:5], v[118:119] op_sel:[1,1] op_sel_hi:[0,1] neg_lo:[0,1]
	v_pk_fma_f32 v[4:5], v[4:5], v[118:119], v[120:121] op_sel_hi:[1,0,1]
	v_pk_mul_f32 v[120:121], v[24:25], v[118:119] op_sel:[0,1] op_sel_hi:[0,0] neg_hi:[1,0]
	v_pk_fma_f32 v[118:119], v[84:85], v[118:119], v[120:121] op_sel_hi:[0,1,1]
	s_mov_b32 s35, s30
	s_waitcnt lgkmcnt(12)
	v_pk_mul_f32 v[120:121], v[6:7], v[118:119] op_sel:[1,1] op_sel_hi:[0,1] neg_lo:[0,1]
	v_pk_fma_f32 v[6:7], v[6:7], v[118:119], v[120:121] op_sel_hi:[1,0,1]
	v_pk_mul_f32 v[120:121], v[24:25], v[118:119] op_sel:[0,1] op_sel_hi:[0,0] neg_hi:[1,0]
	v_pk_fma_f32 v[118:119], v[84:85], v[118:119], v[120:121] op_sel_hi:[0,1,1]
	s_mov_b32 s0, s19
	s_waitcnt lgkmcnt(11)
	v_pk_mul_f32 v[120:121], v[8:9], v[118:119] op_sel:[1,1] op_sel_hi:[0,1] neg_lo:[0,1]
	v_pk_fma_f32 v[8:9], v[8:9], v[118:119], v[120:121] op_sel_hi:[1,0,1]
	v_pk_mul_f32 v[120:121], v[24:25], v[118:119] op_sel:[0,1] op_sel_hi:[0,0] neg_hi:[1,0]
	v_pk_fma_f32 v[118:119], v[84:85], v[118:119], v[120:121] op_sel_hi:[0,1,1]
	s_waitcnt lgkmcnt(0)
	v_pk_mul_f32 v[120:121], v[10:11], v[118:119] op_sel:[1,1] op_sel_hi:[0,1] neg_lo:[0,1]
	v_pk_fma_f32 v[10:11], v[10:11], v[118:119], v[120:121] op_sel_hi:[1,0,1]
	v_pk_mul_f32 v[120:121], v[24:25], v[118:119] op_sel:[0,1] op_sel_hi:[0,0] neg_hi:[1,0]
	v_pk_fma_f32 v[118:119], v[84:85], v[118:119], v[120:121] op_sel_hi:[0,1,1]
	s_barrier
	v_pk_mul_f32 v[120:121], v[12:13], v[118:119] op_sel:[1,1] op_sel_hi:[0,1] neg_lo:[0,1]
	v_pk_fma_f32 v[12:13], v[12:13], v[118:119], v[120:121] op_sel_hi:[1,0,1]
	v_pk_mul_f32 v[120:121], v[24:25], v[118:119] op_sel:[0,1] op_sel_hi:[0,0] neg_hi:[1,0]
	v_pk_fma_f32 v[118:119], v[84:85], v[118:119], v[120:121] op_sel_hi:[0,1,1]
	s_nop 0
	v_pk_mul_f32 v[120:121], v[14:15], v[118:119] op_sel:[1,1] op_sel_hi:[0,1] neg_lo:[0,1]
	v_pk_fma_f32 v[14:15], v[14:15], v[118:119], v[120:121] op_sel_hi:[1,0,1]
	v_pk_mul_f32 v[120:121], v[24:25], v[118:119] op_sel:[0,1] op_sel_hi:[0,0] neg_hi:[1,0]
	v_pk_fma_f32 v[118:119], v[84:85], v[118:119], v[120:121] op_sel_hi:[0,1,1]
	s_nop 0
	v_pk_mul_f32 v[120:121], v[16:17], v[118:119] op_sel:[1,1] op_sel_hi:[0,1] neg_lo:[0,1]
	v_pk_fma_f32 v[16:17], v[16:17], v[118:119], v[120:121] op_sel_hi:[1,0,1]
	v_pk_mul_f32 v[120:121], v[24:25], v[118:119] op_sel:[0,1] op_sel_hi:[0,0] neg_hi:[1,0]
	v_pk_fma_f32 v[118:119], v[84:85], v[118:119], v[120:121] op_sel_hi:[0,1,1]
	s_nop 0
	v_pk_mul_f32 v[120:121], v[18:19], v[118:119] op_sel:[1,1] op_sel_hi:[0,1] neg_lo:[0,1]
	v_pk_fma_f32 v[18:19], v[18:19], v[118:119], v[120:121] op_sel_hi:[1,0,1]
	v_pk_mul_f32 v[120:121], v[24:25], v[118:119] op_sel:[0,1] op_sel_hi:[0,0] neg_hi:[1,0]
	v_pk_fma_f32 v[118:119], v[84:85], v[118:119], v[120:121] op_sel_hi:[0,1,1]
	s_nop 0
	v_pk_mul_f32 v[120:121], v[20:21], v[118:119] op_sel:[1,1] op_sel_hi:[0,1] neg_lo:[0,1]
	v_pk_fma_f32 v[20:21], v[20:21], v[118:119], v[120:121] op_sel_hi:[1,0,1]
	v_pk_mul_f32 v[120:121], v[24:25], v[118:119] op_sel:[0,1] op_sel_hi:[0,0] neg_hi:[1,0]
	v_pk_fma_f32 v[118:119], v[84:85], v[118:119], v[120:121] op_sel_hi:[0,1,1]
	s_nop 0
	v_pk_mul_f32 v[120:121], v[22:23], v[118:119] op_sel:[1,1] op_sel_hi:[0,1] neg_lo:[0,1]
	v_pk_fma_f32 v[22:23], v[22:23], v[118:119], v[120:121] op_sel_hi:[1,0,1]
	v_pk_mul_f32 v[120:121], v[24:25], v[118:119] op_sel:[0,1] op_sel_hi:[0,0] neg_hi:[1,0]
	v_pk_fma_f32 v[118:119], v[84:85], v[118:119], v[120:121] op_sel_hi:[0,1,1]
	s_nop 0
	v_pk_mul_f32 v[120:121], v[26:27], v[118:119] op_sel:[1,1] op_sel_hi:[0,1] neg_lo:[0,1]
	v_pk_fma_f32 v[26:27], v[26:27], v[118:119], v[120:121] op_sel_hi:[1,0,1]
	v_pk_mul_f32 v[120:121], v[24:25], v[118:119] op_sel:[0,1] op_sel_hi:[0,0] neg_hi:[1,0]
	v_pk_fma_f32 v[118:119], v[84:85], v[118:119], v[120:121] op_sel_hi:[0,1,1]
	s_nop 0
	v_pk_mul_f32 v[120:121], v[28:29], v[118:119] op_sel:[1,1] op_sel_hi:[0,1] neg_lo:[0,1]
	v_pk_fma_f32 v[28:29], v[28:29], v[118:119], v[120:121] op_sel_hi:[1,0,1]
	v_pk_mul_f32 v[120:121], v[24:25], v[118:119] op_sel:[0,1] op_sel_hi:[0,0] neg_hi:[1,0]
	v_pk_fma_f32 v[118:119], v[84:85], v[118:119], v[120:121] op_sel_hi:[0,1,1]
	v_pk_mul_f32 v[24:25], v[24:25], v[118:119] op_sel:[0,1] op_sel_hi:[0,0] neg_hi:[1,0]
	v_pk_fma_f32 v[24:25], v[84:85], v[118:119], v[24:25] op_sel_hi:[0,1,1]
	v_pk_mul_f32 v[84:85], v[82:83], v[24:25] op_sel:[1,1] op_sel_hi:[0,1] neg_lo:[0,1]
	v_pk_fma_f32 v[24:25], v[82:83], v[24:25], v[84:85] op_sel_hi:[1,0,1]
	v_pk_add_f32 v[82:83], v[0:1], v[16:17]
	v_pk_add_f32 v[0:1], v[0:1], v[16:17] neg_lo:[0,1] neg_hi:[0,1]
	v_pk_add_f32 v[16:17], v[2:3], v[18:19]
	v_pk_add_f32 v[2:3], v[2:3], v[18:19] neg_lo:[0,1] neg_hi:[0,1]
	v_pk_mul_f32 v[120:121], v[30:31], v[118:119] op_sel:[1,1] op_sel_hi:[0,1] neg_lo:[0,1]
	v_pk_mul_f32 v[18:19], v[2:3], s[18:19]
	v_pk_fma_f32 v[30:31], v[30:31], v[118:119], v[120:121] op_sel_hi:[1,0,1]
	v_pk_fma_f32 v[2:3], v[2:3], s[30:31], v[18:19] op_sel:[0,0,1] op_sel_hi:[1,0,0]
	v_pk_add_f32 v[18:19], v[4:5], v[20:21]
	v_pk_add_f32 v[4:5], v[4:5], v[20:21] neg_lo:[0,1] neg_hi:[0,1]
	s_nop 0
	v_pk_mul_f32 v[20:21], v[4:5], s[10:11]
	s_nop 0
	v_pk_fma_f32 v[4:5], v[4:5], s[14:15], v[20:21] op_sel:[0,0,1] op_sel_hi:[1,0,0]
	v_pk_add_f32 v[20:21], v[6:7], v[22:23]
	v_pk_add_f32 v[6:7], v[6:7], v[22:23] neg_lo:[0,1] neg_hi:[0,1]
	s_nop 0
	v_pk_mul_f32 v[22:23], v[6:7], s[34:35]
	s_nop 0
	v_pk_fma_f32 v[6:7], v[6:7], s[0:1], v[22:23] op_sel:[0,0,1] op_sel_hi:[1,0,0]
	v_pk_add_f32 v[22:23], v[8:9], v[26:27]
	v_pk_add_f32 v[8:9], v[8:9], v[26:27] neg_lo:[0,1] neg_hi:[0,1]
	v_pk_add_f32 v[26:27], v[10:11], v[28:29]
	v_pk_add_f32 v[10:11], v[10:11], v[28:29] neg_lo:[0,1] neg_hi:[0,1]
	s_nop 0
	v_pk_mul_f32 v[28:29], v[10:11], s[34:35]
	s_nop 0
	v_pk_fma_f32 v[10:11], v[10:11], s[0:1], v[28:29] op_sel:[0,0,1] op_sel_hi:[1,0,0] neg_lo:[1,0,0] neg_hi:[1,0,0]
	v_pk_add_f32 v[28:29], v[12:13], v[30:31]
	v_pk_add_f32 v[12:13], v[12:13], v[30:31] neg_lo:[0,1] neg_hi:[0,1]
	s_nop 0
	v_pk_mul_f32 v[30:31], v[12:13], s[10:11]
	s_nop 0
	v_pk_fma_f32 v[12:13], v[12:13], s[14:15], v[30:31] op_sel:[0,0,1] op_sel_hi:[1,0,0] neg_lo:[1,0,0] neg_hi:[1,0,0]
	v_pk_add_f32 v[30:31], v[14:15], v[24:25]
	v_pk_add_f32 v[14:15], v[14:15], v[24:25] neg_lo:[0,1] neg_hi:[0,1]
	s_nop 0
	v_pk_mul_f32 v[24:25], v[14:15], s[18:19]
	s_nop 0
	v_pk_fma_f32 v[14:15], v[14:15], s[30:31], v[24:25] op_sel:[0,0,1] op_sel_hi:[1,0,0] neg_lo:[1,0,0] neg_hi:[1,0,0]
	v_pk_add_f32 v[24:25], v[82:83], v[22:23]
	v_pk_add_f32 v[22:23], v[82:83], v[22:23] neg_lo:[0,1] neg_hi:[0,1]
	v_pk_add_f32 v[82:83], v[16:17], v[26:27]
	v_pk_add_f32 v[16:17], v[16:17], v[26:27] neg_lo:[0,1] neg_hi:[0,1]
	s_nop 0
	v_pk_mul_f32 v[26:27], v[16:17], s[10:11]
	s_nop 0
	v_pk_fma_f32 v[16:17], v[16:17], s[14:15], v[26:27] op_sel:[0,0,1] op_sel_hi:[1,0,0]
	v_pk_add_f32 v[26:27], v[18:19], v[28:29]
	v_pk_add_f32 v[18:19], v[18:19], v[28:29] neg_lo:[0,1] neg_hi:[0,1]
	v_pk_add_f32 v[28:29], v[20:21], v[30:31]
	v_pk_add_f32 v[20:21], v[20:21], v[30:31] neg_lo:[0,1] neg_hi:[0,1]
	s_nop 0
	v_pk_mul_f32 v[30:31], v[20:21], s[10:11]
	s_nop 0
	v_pk_fma_f32 v[20:21], v[20:21], s[14:15], v[30:31] op_sel:[0,0,1] op_sel_hi:[1,0,0] neg_lo:[1,0,0] neg_hi:[1,0,0]
	v_pk_add_f32 v[30:31], v[0:1], v[8:9] op_sel:[0,1] op_sel_hi:[1,0] neg_hi:[0,1]
	v_pk_add_f32 v[0:1], v[0:1], v[8:9] op_sel:[0,1] op_sel_hi:[1,0] neg_lo:[0,1]
	v_pk_add_f32 v[8:9], v[2:3], v[10:11]
	v_pk_add_f32 v[2:3], v[2:3], v[10:11] neg_lo:[0,1] neg_hi:[0,1]
	s_nop 0
	v_pk_mul_f32 v[10:11], v[2:3], s[10:11]
	s_nop 0
	v_pk_fma_f32 v[2:3], v[2:3], s[14:15], v[10:11] op_sel:[0,0,1] op_sel_hi:[1,0,0]
	v_pk_add_f32 v[10:11], v[4:5], v[12:13]
	v_pk_add_f32 v[4:5], v[4:5], v[12:13] neg_lo:[0,1] neg_hi:[0,1]
	v_pk_add_f32 v[12:13], v[6:7], v[14:15]
	v_pk_add_f32 v[6:7], v[6:7], v[14:15] neg_lo:[0,1] neg_hi:[0,1]
	s_nop 0
	v_pk_mul_f32 v[14:15], v[6:7], s[10:11]
	s_nop 0
	v_pk_fma_f32 v[6:7], v[6:7], s[14:15], v[14:15] op_sel:[0,0,1] op_sel_hi:[1,0,0] neg_lo:[1,0,0] neg_hi:[1,0,0]
	v_pk_add_f32 v[14:15], v[24:25], v[26:27]
	v_pk_add_f32 v[24:25], v[24:25], v[26:27] neg_lo:[0,1] neg_hi:[0,1]
	v_pk_add_f32 v[26:27], v[82:83], v[28:29]
	v_pk_add_f32 v[28:29], v[82:83], v[28:29] neg_lo:[0,1] neg_hi:[0,1]
	v_pk_add_f32 v[82:83], v[22:23], v[18:19] op_sel:[0,1] op_sel_hi:[1,0] neg_hi:[0,1]
	v_pk_add_f32 v[18:19], v[22:23], v[18:19] op_sel:[0,1] op_sel_hi:[1,0] neg_lo:[0,1]
	v_pk_add_f32 v[22:23], v[16:17], v[20:21]
	v_pk_add_f32 v[16:17], v[16:17], v[20:21] neg_lo:[0,1] neg_hi:[0,1]
	v_pk_add_f32 v[20:21], v[30:31], v[10:11]
	v_pk_add_f32 v[10:11], v[30:31], v[10:11] neg_lo:[0,1] neg_hi:[0,1]
	v_pk_add_f32 v[30:31], v[8:9], v[12:13]
	v_pk_add_f32 v[8:9], v[8:9], v[12:13] neg_lo:[0,1] neg_hi:[0,1]
	v_pk_add_f32 v[12:13], v[0:1], v[4:5] op_sel:[0,1] op_sel_hi:[1,0] neg_hi:[0,1]
	v_pk_add_f32 v[0:1], v[0:1], v[4:5] op_sel:[0,1] op_sel_hi:[1,0] neg_lo:[0,1]
	v_pk_add_f32 v[4:5], v[2:3], v[6:7]
	v_pk_add_f32 v[2:3], v[2:3], v[6:7] neg_lo:[0,1] neg_hi:[0,1]
	s_nop 0
	v_pk_mul_f32 v[2:3], v[2:3], s[22:23]
	v_pk_add_f32 v[6:7], v[14:15], v[26:27]
	v_pk_add_f32 v[14:15], v[14:15], v[26:27] neg_lo:[0,1] neg_hi:[0,1]
	v_pk_add_f32 v[26:27], v[24:25], v[28:29] op_sel:[0,1] op_sel_hi:[1,0] neg_hi:[0,1]
	v_pk_add_f32 v[24:25], v[24:25], v[28:29] op_sel:[0,1] op_sel_hi:[1,0] neg_lo:[0,1]
	v_pk_add_f32 v[28:29], v[82:83], v[22:23]
	v_pk_add_f32 v[22:23], v[82:83], v[22:23] neg_lo:[0,1] neg_hi:[0,1]
	v_pk_add_f32 v[82:83], v[18:19], v[16:17] op_sel:[0,1] op_sel_hi:[1,0] neg_hi:[0,1]
	v_pk_add_f32 v[16:17], v[18:19], v[16:17] op_sel:[0,1] op_sel_hi:[1,0] neg_lo:[0,1]
	v_pk_add_f32 v[18:19], v[20:21], v[30:31]
	v_pk_add_f32 v[20:21], v[20:21], v[30:31] neg_lo:[0,1] neg_hi:[0,1]
	v_pk_add_f32 v[30:31], v[10:11], v[8:9] op_sel:[0,1] op_sel_hi:[1,0] neg_hi:[0,1]
	v_pk_add_f32 v[8:9], v[10:11], v[8:9] op_sel:[0,1] op_sel_hi:[1,0] neg_lo:[0,1]
	v_pk_add_f32 v[10:11], v[12:13], v[4:5]
	v_pk_add_f32 v[4:5], v[12:13], v[4:5] neg_lo:[0,1] neg_hi:[0,1]
	v_pk_add_f32 v[12:13], v[0:1], v[2:3] op_sel:[0,1] op_sel_hi:[1,0]
	v_pk_add_f32 v[0:1], v[0:1], v[2:3] op_sel:[0,1] op_sel_hi:[1,0] neg_lo:[0,1] neg_hi:[0,1]
	v_lshlrev_b32_e32 v2, 4, v37
	v_and_or_b32 v2, v2, s7, v47
	v_ashrrev_i32_e32 v3, 4, v2
	v_lshlrev_b32_e32 v3, 3, v3
	v_lshlrev_b32_e32 v2, 3, v2
	v_add3_u32 v2, 0, v3, v2
	v_add_u32_e32 v3, 0x800, v2
	v_mov_b32_e32 v37, v32
	ds_write2_b64 v2, v[6:7], v[18:19] offset1:34
	ds_write2_b64 v3, v[14:15], v[20:21] offset0:16 offset1:50
	ds_write2_b64 v2, v[26:27], v[30:31] offset0:136 offset1:170
	ds_write2_b64 v3, v[24:25], v[8:9] offset0:152 offset1:186
	ds_write2_b64 v2, v[28:29], v[10:11] offset0:68 offset1:102
	ds_write2_b64 v3, v[22:23], v[4:5] offset0:84 offset1:118
	ds_write2_b64 v2, v[82:83], v[12:13] offset0:204 offset1:238
	ds_write2_b64 v3, v[16:17], v[0:1] offset0:220 offset1:254
	s_waitcnt lgkmcnt(0)
	s_barrier
	v_lshl_add_u64 v[224:225], v[78:79], 0, v[172:173]
	s_mov_b64 s[100:101], 0x80000
	v_lshl_add_u64 v[228:229], v[224:225], 0, s[100:101]
	global_load_dword v226, v[228:229], off
	s_mov_b64 s[100:101], 0x140000
	v_lshl_add_u64 v[228:229], v[224:225], 0, s[100:101]
	global_load_dword v226, v[228:229], off
	s_nop 0
	v_and_b32_e32 v47, 0x1ff, v37
	v_cvt_f32_u32_e32 v24, v47
	v_ashrrev_i32_e32 v0, 4, v37
	v_lshlrev_b32_e32 v0, 3, v0
	v_lshlrev_b32_e32 v1, 3, v37
	v_mul_f32_e32 v81, 0x39000000, v24
	v_sin_f32_e32 v24, v81
	v_cos_f32_e32 v84, v81
	v_add3_u32 v25, 0, v0, v1
	ds_read_b64 v[0:1], v25
	ds_read_b64 v[2:3], v25 offset:4352
	ds_read_b64 v[4:5], v25 offset:8704
	ds_read_b64 v[6:7], v25 offset:13056
	ds_read_b64 v[8:9], v25 offset:17408
	ds_read_b64 v[10:11], v25 offset:21760
	ds_read_b64 v[12:13], v25 offset:26112
	ds_read_b64 v[14:15], v25 offset:30464
	v_xor_b32_e32 v85, 0x80000000, v24
	s_waitcnt lgkmcnt(6)
	v_pk_mul_f32 v[118:119], v[2:3], v[24:25] op_sel:[1,0] op_sel_hi:[0,0] neg_hi:[0,1]
	v_pk_fma_f32 v[2:3], v[2:3], v[84:85], v[118:119] op_sel_hi:[1,0,1]
	v_pk_mul_f32 v[118:119], v[24:25], v[84:85] op_sel:[0,1] op_sel_hi:[0,0] neg_hi:[1,0]
	v_pk_fma_f32 v[118:119], v[84:85], v[84:85], v[118:119] op_sel_hi:[0,1,1]
	ds_read_b64 v[16:17], v25 offset:34816
	ds_read_b64 v[18:19], v25 offset:39168
	ds_read_b64 v[20:21], v25 offset:43520
	ds_read_b64 v[22:23], v25 offset:47872
	s_waitcnt lgkmcnt(9)
	v_pk_mul_f32 v[120:121], v[4:5], v[118:119] op_sel:[1,1] op_sel_hi:[0,1] neg_lo:[0,1]
	v_pk_fma_f32 v[4:5], v[4:5], v[118:119], v[120:121] op_sel_hi:[1,0,1]
	v_pk_mul_f32 v[120:121], v[24:25], v[118:119] op_sel:[0,1] op_sel_hi:[0,0] neg_hi:[1,0]
	v_pk_fma_f32 v[118:119], v[84:85], v[118:119], v[120:121] op_sel_hi:[0,1,1]
	ds_read_b64 v[26:27], v25 offset:52224
	ds_read_b64 v[28:29], v25 offset:56576
	ds_read_b64 v[30:31], v25 offset:60928
	ds_read_b64 v[82:83], v25 offset:65280
	s_waitcnt lgkmcnt(12)
	v_pk_mul_f32 v[120:121], v[6:7], v[118:119] op_sel:[1,1] op_sel_hi:[0,1] neg_lo:[0,1]
	v_pk_fma_f32 v[6:7], v[6:7], v[118:119], v[120:121] op_sel_hi:[1,0,1]
	v_pk_mul_f32 v[120:121], v[24:25], v[118:119] op_sel:[0,1] op_sel_hi:[0,0] neg_hi:[1,0]
	v_pk_fma_f32 v[118:119], v[84:85], v[118:119], v[120:121] op_sel_hi:[0,1,1]
	s_waitcnt lgkmcnt(0)
	v_pk_mul_f32 v[120:121], v[8:9], v[118:119] op_sel:[1,1] op_sel_hi:[0,1] neg_lo:[0,1]
	v_pk_fma_f32 v[8:9], v[8:9], v[118:119], v[120:121] op_sel_hi:[1,0,1]
	v_pk_mul_f32 v[120:121], v[24:25], v[118:119] op_sel:[0,1] op_sel_hi:[0,0] neg_hi:[1,0]
	v_pk_fma_f32 v[118:119], v[84:85], v[118:119], v[120:121] op_sel_hi:[0,1,1]
	s_barrier
	v_pk_mul_f32 v[120:121], v[10:11], v[118:119] op_sel:[1,1] op_sel_hi:[0,1] neg_lo:[0,1]
	v_pk_fma_f32 v[10:11], v[10:11], v[118:119], v[120:121] op_sel_hi:[1,0,1]
	v_pk_mul_f32 v[120:121], v[24:25], v[118:119] op_sel:[0,1] op_sel_hi:[0,0] neg_hi:[1,0]
	v_pk_fma_f32 v[118:119], v[84:85], v[118:119], v[120:121] op_sel_hi:[0,1,1]
	s_nop 0
	v_pk_mul_f32 v[120:121], v[12:13], v[118:119] op_sel:[1,1] op_sel_hi:[0,1] neg_lo:[0,1]
	v_pk_fma_f32 v[12:13], v[12:13], v[118:119], v[120:121] op_sel_hi:[1,0,1]
	v_pk_mul_f32 v[120:121], v[24:25], v[118:119] op_sel:[0,1] op_sel_hi:[0,0] neg_hi:[1,0]
	v_pk_fma_f32 v[118:119], v[84:85], v[118:119], v[120:121] op_sel_hi:[0,1,1]
	s_nop 0
	v_pk_mul_f32 v[120:121], v[14:15], v[118:119] op_sel:[1,1] op_sel_hi:[0,1] neg_lo:[0,1]
	v_pk_fma_f32 v[14:15], v[14:15], v[118:119], v[120:121] op_sel_hi:[1,0,1]
	v_pk_mul_f32 v[120:121], v[24:25], v[118:119] op_sel:[0,1] op_sel_hi:[0,0] neg_hi:[1,0]
	v_pk_fma_f32 v[118:119], v[84:85], v[118:119], v[120:121] op_sel_hi:[0,1,1]
	s_nop 0
	v_pk_mul_f32 v[120:121], v[16:17], v[118:119] op_sel:[1,1] op_sel_hi:[0,1] neg_lo:[0,1]
	v_pk_fma_f32 v[16:17], v[16:17], v[118:119], v[120:121] op_sel_hi:[1,0,1]
	v_pk_mul_f32 v[120:121], v[24:25], v[118:119] op_sel:[0,1] op_sel_hi:[0,0] neg_hi:[1,0]
	v_pk_fma_f32 v[118:119], v[84:85], v[118:119], v[120:121] op_sel_hi:[0,1,1]
	s_nop 0
	v_pk_mul_f32 v[120:121], v[18:19], v[118:119] op_sel:[1,1] op_sel_hi:[0,1] neg_lo:[0,1]
	v_pk_fma_f32 v[18:19], v[18:19], v[118:119], v[120:121] op_sel_hi:[1,0,1]
	v_pk_mul_f32 v[120:121], v[24:25], v[118:119] op_sel:[0,1] op_sel_hi:[0,0] neg_hi:[1,0]
	v_pk_fma_f32 v[118:119], v[84:85], v[118:119], v[120:121] op_sel_hi:[0,1,1]
	s_nop 0
	v_pk_mul_f32 v[120:121], v[20:21], v[118:119] op_sel:[1,1] op_sel_hi:[0,1] neg_lo:[0,1]
	v_pk_fma_f32 v[20:21], v[20:21], v[118:119], v[120:121] op_sel_hi:[1,0,1]
	v_pk_mul_f32 v[120:121], v[24:25], v[118:119] op_sel:[0,1] op_sel_hi:[0,0] neg_hi:[1,0]
	v_pk_fma_f32 v[118:119], v[84:85], v[118:119], v[120:121] op_sel_hi:[0,1,1]
	s_nop 0
	v_pk_mul_f32 v[120:121], v[22:23], v[118:119] op_sel:[1,1] op_sel_hi:[0,1] neg_lo:[0,1]
	v_pk_fma_f32 v[22:23], v[22:23], v[118:119], v[120:121] op_sel_hi:[1,0,1]
	v_pk_mul_f32 v[120:121], v[24:25], v[118:119] op_sel:[0,1] op_sel_hi:[0,0] neg_hi:[1,0]
	v_pk_fma_f32 v[118:119], v[84:85], v[118:119], v[120:121] op_sel_hi:[0,1,1]
	s_nop 0
	v_pk_mul_f32 v[120:121], v[26:27], v[118:119] op_sel:[1,1] op_sel_hi:[0,1] neg_lo:[0,1]
	v_pk_fma_f32 v[26:27], v[26:27], v[118:119], v[120:121] op_sel_hi:[1,0,1]
	v_pk_mul_f32 v[120:121], v[24:25], v[118:119] op_sel:[0,1] op_sel_hi:[0,0] neg_hi:[1,0]
	v_pk_fma_f32 v[118:119], v[84:85], v[118:119], v[120:121] op_sel_hi:[0,1,1]
	s_nop 0
	v_pk_mul_f32 v[120:121], v[28:29], v[118:119] op_sel:[1,1] op_sel_hi:[0,1] neg_lo:[0,1]
	v_pk_fma_f32 v[28:29], v[28:29], v[118:119], v[120:121] op_sel_hi:[1,0,1]
	v_pk_mul_f32 v[120:121], v[24:25], v[118:119] op_sel:[0,1] op_sel_hi:[0,0] neg_hi:[1,0]
	v_pk_fma_f32 v[118:119], v[84:85], v[118:119], v[120:121] op_sel_hi:[0,1,1]
	v_pk_mul_f32 v[24:25], v[24:25], v[118:119] op_sel:[0,1] op_sel_hi:[0,0] neg_hi:[1,0]
	v_pk_fma_f32 v[24:25], v[84:85], v[118:119], v[24:25] op_sel_hi:[0,1,1]
	v_pk_mul_f32 v[84:85], v[82:83], v[24:25] op_sel:[1,1] op_sel_hi:[0,1] neg_lo:[0,1]
	v_pk_fma_f32 v[24:25], v[82:83], v[24:25], v[84:85] op_sel_hi:[1,0,1]
	v_pk_add_f32 v[82:83], v[0:1], v[16:17]
	v_pk_add_f32 v[0:1], v[0:1], v[16:17] neg_lo:[0,1] neg_hi:[0,1]
	v_pk_add_f32 v[16:17], v[2:3], v[18:19]
	v_pk_add_f32 v[2:3], v[2:3], v[18:19] neg_lo:[0,1] neg_hi:[0,1]
	v_pk_mul_f32 v[120:121], v[30:31], v[118:119] op_sel:[1,1] op_sel_hi:[0,1] neg_lo:[0,1]
	v_pk_mul_f32 v[18:19], v[2:3], s[18:19]
	v_pk_fma_f32 v[30:31], v[30:31], v[118:119], v[120:121] op_sel_hi:[1,0,1]
	v_pk_fma_f32 v[2:3], v[2:3], s[30:31], v[18:19] op_sel:[0,0,1] op_sel_hi:[1,0,0]
	v_pk_add_f32 v[18:19], v[4:5], v[20:21]
	v_pk_add_f32 v[4:5], v[4:5], v[20:21] neg_lo:[0,1] neg_hi:[0,1]
	s_nop 0
	v_pk_mul_f32 v[20:21], v[4:5], s[10:11]
	s_nop 0
	v_pk_fma_f32 v[4:5], v[4:5], s[14:15], v[20:21] op_sel:[0,0,1] op_sel_hi:[1,0,0]
	v_pk_add_f32 v[20:21], v[6:7], v[22:23]
	v_pk_add_f32 v[6:7], v[6:7], v[22:23] neg_lo:[0,1] neg_hi:[0,1]
	s_nop 0
	v_pk_mul_f32 v[22:23], v[6:7], s[34:35]
	s_nop 0
	v_pk_fma_f32 v[6:7], v[6:7], s[0:1], v[22:23] op_sel:[0,0,1] op_sel_hi:[1,0,0]
	v_pk_add_f32 v[22:23], v[8:9], v[26:27]
	v_pk_add_f32 v[8:9], v[8:9], v[26:27] neg_lo:[0,1] neg_hi:[0,1]
	v_pk_add_f32 v[26:27], v[10:11], v[28:29]
	v_pk_add_f32 v[10:11], v[10:11], v[28:29] neg_lo:[0,1] neg_hi:[0,1]
	s_nop 0
	v_pk_mul_f32 v[28:29], v[10:11], s[34:35]
	s_nop 0
	v_pk_fma_f32 v[10:11], v[10:11], s[0:1], v[28:29] op_sel:[0,0,1] op_sel_hi:[1,0,0] neg_lo:[1,0,0] neg_hi:[1,0,0]
	v_pk_add_f32 v[28:29], v[12:13], v[30:31]
	v_pk_add_f32 v[12:13], v[12:13], v[30:31] neg_lo:[0,1] neg_hi:[0,1]
	s_nop 0
	v_pk_mul_f32 v[30:31], v[12:13], s[10:11]
	s_nop 0
	v_pk_fma_f32 v[12:13], v[12:13], s[14:15], v[30:31] op_sel:[0,0,1] op_sel_hi:[1,0,0] neg_lo:[1,0,0] neg_hi:[1,0,0]
	v_pk_add_f32 v[30:31], v[14:15], v[24:25]
	v_pk_add_f32 v[14:15], v[14:15], v[24:25] neg_lo:[0,1] neg_hi:[0,1]
	s_nop 0
	v_pk_mul_f32 v[24:25], v[14:15], s[18:19]
	s_nop 0
	v_pk_fma_f32 v[14:15], v[14:15], s[30:31], v[24:25] op_sel:[0,0,1] op_sel_hi:[1,0,0] neg_lo:[1,0,0] neg_hi:[1,0,0]
	v_pk_add_f32 v[24:25], v[82:83], v[22:23]
	v_pk_add_f32 v[22:23], v[82:83], v[22:23] neg_lo:[0,1] neg_hi:[0,1]
	v_pk_add_f32 v[82:83], v[16:17], v[26:27]
	v_pk_add_f32 v[16:17], v[16:17], v[26:27] neg_lo:[0,1] neg_hi:[0,1]
	s_nop 0
	v_pk_mul_f32 v[26:27], v[16:17], s[10:11]
	s_nop 0
	v_pk_fma_f32 v[16:17], v[16:17], s[14:15], v[26:27] op_sel:[0,0,1] op_sel_hi:[1,0,0]
	v_pk_add_f32 v[26:27], v[18:19], v[28:29]
	v_pk_add_f32 v[18:19], v[18:19], v[28:29] neg_lo:[0,1] neg_hi:[0,1]
	v_pk_add_f32 v[28:29], v[20:21], v[30:31]
	v_pk_add_f32 v[20:21], v[20:21], v[30:31] neg_lo:[0,1] neg_hi:[0,1]
	s_nop 0
	v_pk_mul_f32 v[30:31], v[20:21], s[10:11]
	s_nop 0
	v_pk_fma_f32 v[20:21], v[20:21], s[14:15], v[30:31] op_sel:[0,0,1] op_sel_hi:[1,0,0] neg_lo:[1,0,0] neg_hi:[1,0,0]
	v_pk_add_f32 v[30:31], v[0:1], v[8:9] op_sel:[0,1] op_sel_hi:[1,0] neg_hi:[0,1]
	v_pk_add_f32 v[0:1], v[0:1], v[8:9] op_sel:[0,1] op_sel_hi:[1,0] neg_lo:[0,1]
	v_pk_add_f32 v[8:9], v[2:3], v[10:11]
	v_pk_add_f32 v[2:3], v[2:3], v[10:11] neg_lo:[0,1] neg_hi:[0,1]
	s_nop 0
	v_pk_mul_f32 v[10:11], v[2:3], s[10:11]
	s_nop 0
	v_pk_fma_f32 v[2:3], v[2:3], s[14:15], v[10:11] op_sel:[0,0,1] op_sel_hi:[1,0,0]
	v_pk_add_f32 v[10:11], v[4:5], v[12:13]
	v_pk_add_f32 v[4:5], v[4:5], v[12:13] neg_lo:[0,1] neg_hi:[0,1]
	v_pk_add_f32 v[12:13], v[6:7], v[14:15]
	v_pk_add_f32 v[6:7], v[6:7], v[14:15] neg_lo:[0,1] neg_hi:[0,1]
	s_nop 0
	v_pk_mul_f32 v[14:15], v[6:7], s[10:11]
	s_nop 0
	v_pk_fma_f32 v[6:7], v[6:7], s[14:15], v[14:15] op_sel:[0,0,1] op_sel_hi:[1,0,0] neg_lo:[1,0,0] neg_hi:[1,0,0]
	v_pk_add_f32 v[14:15], v[24:25], v[26:27]
	v_pk_add_f32 v[24:25], v[24:25], v[26:27] neg_lo:[0,1] neg_hi:[0,1]
	v_pk_add_f32 v[26:27], v[82:83], v[28:29]
	v_pk_add_f32 v[28:29], v[82:83], v[28:29] neg_lo:[0,1] neg_hi:[0,1]
	v_pk_add_f32 v[82:83], v[22:23], v[18:19] op_sel:[0,1] op_sel_hi:[1,0] neg_hi:[0,1]
	v_pk_add_f32 v[18:19], v[22:23], v[18:19] op_sel:[0,1] op_sel_hi:[1,0] neg_lo:[0,1]
	v_pk_add_f32 v[22:23], v[16:17], v[20:21]
	v_pk_add_f32 v[16:17], v[16:17], v[20:21] neg_lo:[0,1] neg_hi:[0,1]
	v_pk_add_f32 v[20:21], v[30:31], v[10:11]
	v_pk_add_f32 v[10:11], v[30:31], v[10:11] neg_lo:[0,1] neg_hi:[0,1]
	v_pk_add_f32 v[30:31], v[8:9], v[12:13]
	v_pk_add_f32 v[8:9], v[8:9], v[12:13] neg_lo:[0,1] neg_hi:[0,1]
	v_pk_add_f32 v[12:13], v[0:1], v[4:5] op_sel:[0,1] op_sel_hi:[1,0] neg_hi:[0,1]
	v_pk_add_f32 v[0:1], v[0:1], v[4:5] op_sel:[0,1] op_sel_hi:[1,0] neg_lo:[0,1]
	v_pk_add_f32 v[4:5], v[2:3], v[6:7]
	v_pk_add_f32 v[2:3], v[2:3], v[6:7] neg_lo:[0,1] neg_hi:[0,1]
	s_nop 0
	v_pk_mul_f32 v[2:3], v[2:3], s[22:23]
	v_pk_add_f32 v[6:7], v[14:15], v[26:27]
	v_pk_add_f32 v[14:15], v[14:15], v[26:27] neg_lo:[0,1] neg_hi:[0,1]
	v_pk_add_f32 v[26:27], v[24:25], v[28:29] op_sel:[0,1] op_sel_hi:[1,0] neg_hi:[0,1]
	v_pk_add_f32 v[24:25], v[24:25], v[28:29] op_sel:[0,1] op_sel_hi:[1,0] neg_lo:[0,1]
	v_pk_add_f32 v[28:29], v[82:83], v[22:23]
	v_pk_add_f32 v[22:23], v[82:83], v[22:23] neg_lo:[0,1] neg_hi:[0,1]
	v_pk_add_f32 v[82:83], v[18:19], v[16:17] op_sel:[0,1] op_sel_hi:[1,0] neg_hi:[0,1]
	v_pk_add_f32 v[16:17], v[18:19], v[16:17] op_sel:[0,1] op_sel_hi:[1,0] neg_lo:[0,1]
	v_pk_add_f32 v[18:19], v[20:21], v[30:31]
	v_pk_add_f32 v[20:21], v[20:21], v[30:31] neg_lo:[0,1] neg_hi:[0,1]
	v_pk_add_f32 v[30:31], v[10:11], v[8:9] op_sel:[0,1] op_sel_hi:[1,0] neg_hi:[0,1]
	v_pk_add_f32 v[8:9], v[10:11], v[8:9] op_sel:[0,1] op_sel_hi:[1,0] neg_lo:[0,1]
	v_pk_add_f32 v[10:11], v[12:13], v[4:5]
	v_pk_add_f32 v[4:5], v[12:13], v[4:5] neg_lo:[0,1] neg_hi:[0,1]
	v_pk_add_f32 v[12:13], v[0:1], v[2:3] op_sel:[0,1] op_sel_hi:[1,0]
	v_pk_add_f32 v[0:1], v[0:1], v[2:3] op_sel:[0,1] op_sel_hi:[1,0] neg_lo:[0,1] neg_hi:[0,1]
	v_lshlrev_b32_e32 v2, 4, v37
	v_and_or_b32 v2, v2, s15, v47
	v_ashrrev_i32_e32 v3, 4, v2
	v_lshlrev_b32_e32 v3, 3, v3
	v_lshlrev_b32_e32 v2, 3, v2
	v_add3_u32 v2, 0, v3, v2
	ds_write_b64 v2, v[6:7]
	ds_write_b64 v2, v[14:15] offset:34816
	ds_write_b64 v2, v[26:27] offset:17408
	ds_write_b64 v2, v[24:25] offset:52224
	ds_write_b64 v2, v[28:29] offset:8704
	ds_write_b64 v2, v[22:23] offset:43520
	ds_write_b64 v2, v[82:83] offset:26112
	ds_write_b64 v2, v[16:17] offset:60928
	ds_write_b64 v2, v[18:19] offset:4352
	ds_write_b64 v2, v[20:21] offset:39168
	ds_write_b64 v2, v[30:31] offset:21760
	ds_write_b64 v2, v[8:9] offset:56576
	ds_write_b64 v2, v[10:11] offset:13056
	ds_write_b64 v2, v[4:5] offset:47872
	ds_write_b64 v2, v[12:13] offset:30464
	ds_write_b64 v2, v[0:1] offset:65280
	s_waitcnt lgkmcnt(0)
	s_barrier
	s_and_saveexec_b64 s[0:1], s[42:43]
	s_cbranch_execz .LBB0_500
	v_lshl_add_u64 v[2:3], v[78:79], 0, v[172:173]
	s_mov_b64 s[4:5], 0x80000
	v_lshl_add_u64 v[0:1], v[2:3], 0, s[4:5]
	v_add_co_u32_e32 v2, vcc, 0x80000, v2
	v_cmp_ne_u32_e64 s[42:43], 0, v39
	s_nop 0
	v_addc_co_u32_e32 v3, vcc, 0, v3, vcc
	global_load_dwordx4 v[12:15], v[2:3], off
	global_load_dwordx4 v[8:11], v[0:1], off offset:16
	v_mov_b32_e32 v19, 0
	v_mov_b32_e32 v21, 0
	v_mov_b32_e32 v33, 0
	s_and_saveexec_b64 s[4:5], s[42:43]
	s_cbranch_execz .LBB0_493
	global_load_ushort v33, v[0:1], off offset:-2

.LBB0_623:
	s_or_b64 exec, exec, s[4:5]
	v_mov_b32_e32 v41, v32
	s_waitcnt lgkmcnt(0)
	s_barrier
	s_mov_b32 s11, s14
	v_and_b32_e32 v98, 31, v41
	v_cvt_f32_ubyte0_e32 v24, v98
	v_mul_f32_e32 v92, 0x3b000000, v24
	v_sin_f32_e32 v24, v92
	v_ashrrev_i32_e32 v0, 4, v41
	v_lshlrev_b32_e32 v0, 3, v0
	v_lshlrev_b32_e32 v1, 3, v41
	v_cos_f32_e32 v92, v92
	v_add3_u32 v25, 0, v0, v1
	ds_read_b64 v[0:1], v25
	ds_read_b64 v[2:3], v25 offset:4352
	ds_read_b64 v[4:5], v25 offset:8704
	ds_read_b64 v[6:7], v25 offset:13056
	ds_read_b64 v[8:9], v25 offset:17408
	ds_read_b64 v[10:11], v25 offset:21760
	ds_read_b64 v[12:13], v25 offset:26112
	ds_read_b64 v[14:15], v25 offset:30464
	ds_read_b64 v[16:17], v25 offset:34816
	ds_read_b64 v[18:19], v25 offset:39168
	ds_read_b64 v[20:21], v25 offset:43520
	ds_read_b64 v[22:23], v25 offset:47872
	v_xor_b32_e32 v93, 0x80000000, v24
	s_waitcnt lgkmcnt(10)
	v_pk_mul_f32 v[94:95], v[2:3], v[24:25] op_sel:[1,0] op_sel_hi:[0,0] neg_hi:[0,1]
	v_pk_fma_f32 v[2:3], v[2:3], v[92:93], v[94:95] op_sel_hi:[1,0,1]
	v_pk_mul_f32 v[94:95], v[24:25], v[92:93] op_sel:[0,1] op_sel_hi:[0,0] neg_hi:[1,0]
	v_pk_fma_f32 v[94:95], v[92:93], v[92:93], v[94:95] op_sel_hi:[0,1,1]
	ds_read_b64 v[26:27], v25 offset:52224
	ds_read_b64 v[28:29], v25 offset:56576
	ds_read_b64 v[30:31], v25 offset:60928
	ds_read_b64 v[86:87], v25 offset:65280
	s_waitcnt lgkmcnt(13)
	v_pk_mul_f32 v[96:97], v[4:5], v[94:95] op_sel:[1,1] op_sel_hi:[0,1] neg_lo:[0,1]
	v_pk_fma_f32 v[4:5], v[4:5], v[94:95], v[96:97] op_sel_hi:[1,0,1]
	v_pk_mul_f32 v[96:97], v[24:25], v[94:95] op_sel:[0,1] op_sel_hi:[0,0] neg_hi:[1,0]
	v_pk_fma_f32 v[94:95], v[92:93], v[94:95], v[96:97] op_sel_hi:[0,1,1]
	s_mov_b32 s35, s30
	s_waitcnt lgkmcnt(12)
	v_pk_mul_f32 v[96:97], v[6:7], v[94:95] op_sel:[1,1] op_sel_hi:[0,1] neg_lo:[0,1]
	v_pk_fma_f32 v[6:7], v[6:7], v[94:95], v[96:97] op_sel_hi:[1,0,1]
	v_pk_mul_f32 v[96:97], v[24:25], v[94:95] op_sel:[0,1] op_sel_hi:[0,0] neg_hi:[1,0]
	v_pk_fma_f32 v[94:95], v[92:93], v[94:95], v[96:97] op_sel_hi:[0,1,1]
	s_mov_b32 s26, s19
	s_waitcnt lgkmcnt(11)
	v_pk_mul_f32 v[96:97], v[8:9], v[94:95] op_sel:[1,1] op_sel_hi:[0,1] neg_lo:[0,1]
	v_pk_fma_f32 v[8:9], v[8:9], v[94:95], v[96:97] op_sel_hi:[1,0,1]
	v_pk_mul_f32 v[96:97], v[24:25], v[94:95] op_sel:[0,1] op_sel_hi:[0,0] neg_hi:[1,0]
	v_pk_fma_f32 v[94:95], v[92:93], v[94:95], v[96:97] op_sel_hi:[0,1,1]
	s_waitcnt lgkmcnt(0)
	v_pk_mul_f32 v[96:97], v[10:11], v[94:95] op_sel:[1,1] op_sel_hi:[0,1] neg_lo:[0,1]
	v_pk_fma_f32 v[10:11], v[10:11], v[94:95], v[96:97] op_sel_hi:[1,0,1]
	v_pk_mul_f32 v[96:97], v[24:25], v[94:95] op_sel:[0,1] op_sel_hi:[0,0] neg_hi:[1,0]
	v_pk_fma_f32 v[94:95], v[92:93], v[94:95], v[96:97] op_sel_hi:[0,1,1]
	s_barrier
	v_pk_mul_f32 v[96:97], v[12:13], v[94:95] op_sel:[1,1] op_sel_hi:[0,1] neg_lo:[0,1]
	v_pk_fma_f32 v[12:13], v[12:13], v[94:95], v[96:97] op_sel_hi:[1,0,1]
	v_pk_mul_f32 v[96:97], v[24:25], v[94:95] op_sel:[0,1] op_sel_hi:[0,0] neg_hi:[1,0]
	v_pk_fma_f32 v[94:95], v[92:93], v[94:95], v[96:97] op_sel_hi:[0,1,1]
	s_nop 0
	v_pk_mul_f32 v[96:97], v[14:15], v[94:95] op_sel:[1,1] op_sel_hi:[0,1] neg_lo:[0,1]
	v_pk_fma_f32 v[14:15], v[14:15], v[94:95], v[96:97] op_sel_hi:[1,0,1]
	v_pk_mul_f32 v[96:97], v[24:25], v[94:95] op_sel:[0,1] op_sel_hi:[0,0] neg_hi:[1,0]
	v_pk_fma_f32 v[94:95], v[92:93], v[94:95], v[96:97] op_sel_hi:[0,1,1]
	s_nop 0
	v_pk_mul_f32 v[96:97], v[16:17], v[94:95] op_sel:[1,1] op_sel_hi:[0,1] neg_lo:[0,1]
	v_pk_fma_f32 v[16:17], v[16:17], v[94:95], v[96:97] op_sel_hi:[1,0,1]
	v_pk_mul_f32 v[96:97], v[24:25], v[94:95] op_sel:[0,1] op_sel_hi:[0,0] neg_hi:[1,0]
	v_pk_fma_f32 v[94:95], v[92:93], v[94:95], v[96:97] op_sel_hi:[0,1,1]
	s_nop 0
	v_pk_mul_f32 v[96:97], v[18:19], v[94:95] op_sel:[1,1] op_sel_hi:[0,1] neg_lo:[0,1]
	v_pk_fma_f32 v[18:19], v[18:19], v[94:95], v[96:97] op_sel_hi:[1,0,1]
	v_pk_mul_f32 v[96:97], v[24:25], v[94:95] op_sel:[0,1] op_sel_hi:[0,0] neg_hi:[1,0]
	v_pk_fma_f32 v[94:95], v[92:93], v[94:95], v[96:97] op_sel_hi:[0,1,1]
	s_nop 0
	v_pk_mul_f32 v[96:97], v[20:21], v[94:95] op_sel:[1,1] op_sel_hi:[0,1] neg_lo:[0,1]
	v_pk_fma_f32 v[20:21], v[20:21], v[94:95], v[96:97] op_sel_hi:[1,0,1]
	v_pk_mul_f32 v[96:97], v[24:25], v[94:95] op_sel:[0,1] op_sel_hi:[0,0] neg_hi:[1,0]
	v_pk_fma_f32 v[94:95], v[92:93], v[94:95], v[96:97] op_sel_hi:[0,1,1]
	s_nop 0
	v_pk_mul_f32 v[96:97], v[22:23], v[94:95] op_sel:[1,1] op_sel_hi:[0,1] neg_lo:[0,1]
	v_pk_fma_f32 v[22:23], v[22:23], v[94:95], v[96:97] op_sel_hi:[1,0,1]
	v_pk_mul_f32 v[96:97], v[24:25], v[94:95] op_sel:[0,1] op_sel_hi:[0,0] neg_hi:[1,0]
	v_pk_fma_f32 v[94:95], v[92:93], v[94:95], v[96:97] op_sel_hi:[0,1,1]
	s_nop 0
	v_pk_mul_f32 v[96:97], v[26:27], v[94:95] op_sel:[1,1] op_sel_hi:[0,1] neg_lo:[0,1]
	v_pk_fma_f32 v[26:27], v[26:27], v[94:95], v[96:97] op_sel_hi:[1,0,1]
	v_pk_mul_f32 v[96:97], v[24:25], v[94:95] op_sel:[0,1] op_sel_hi:[0,0] neg_hi:[1,0]
	v_pk_fma_f32 v[94:95], v[92:93], v[94:95], v[96:97] op_sel_hi:[0,1,1]
	s_nop 0
	v_pk_mul_f32 v[96:97], v[28:29], v[94:95] op_sel:[1,1] op_sel_hi:[0,1] neg_lo:[0,1]
	v_pk_fma_f32 v[28:29], v[28:29], v[94:95], v[96:97] op_sel_hi:[1,0,1]
	v_pk_mul_f32 v[96:97], v[24:25], v[94:95] op_sel:[0,1] op_sel_hi:[0,0] neg_hi:[1,0]
	v_pk_fma_f32 v[94:95], v[92:93], v[94:95], v[96:97] op_sel_hi:[0,1,1]
	v_pk_mul_f32 v[24:25], v[24:25], v[94:95] op_sel:[0,1] op_sel_hi:[0,0] neg_hi:[1,0]
	v_pk_fma_f32 v[24:25], v[92:93], v[94:95], v[24:25] op_sel_hi:[0,1,1]
	v_pk_mul_f32 v[92:93], v[86:87], v[24:25] op_sel:[1,1] op_sel_hi:[0,1] neg_lo:[0,1]
	v_pk_fma_f32 v[24:25], v[86:87], v[24:25], v[92:93] op_sel_hi:[1,0,1]
	v_pk_add_f32 v[86:87], v[0:1], v[16:17]
	v_pk_add_f32 v[0:1], v[0:1], v[16:17] neg_lo:[0,1] neg_hi:[0,1]
	v_pk_add_f32 v[16:17], v[2:3], v[18:19]
	v_pk_add_f32 v[2:3], v[2:3], v[18:19] neg_lo:[0,1] neg_hi:[0,1]
	v_pk_mul_f32 v[96:97], v[30:31], v[94:95] op_sel:[1,1] op_sel_hi:[0,1] neg_lo:[0,1]
	v_pk_mul_f32 v[18:19], v[2:3], s[18:19]
	v_pk_fma_f32 v[30:31], v[30:31], v[94:95], v[96:97] op_sel_hi:[1,0,1]
	v_pk_fma_f32 v[2:3], v[2:3], s[30:31], v[18:19] op_sel:[0,0,1] op_sel_hi:[1,0,0]
	v_pk_add_f32 v[18:19], v[4:5], v[20:21]
	v_pk_add_f32 v[4:5], v[4:5], v[20:21] neg_lo:[0,1] neg_hi:[0,1]
	s_nop 0
	v_pk_mul_f32 v[20:21], v[4:5], s[10:11]
	s_nop 0
	v_pk_fma_f32 v[4:5], v[4:5], s[14:15], v[20:21] op_sel:[0,0,1] op_sel_hi:[1,0,0]
	v_pk_add_f32 v[20:21], v[6:7], v[22:23]
	v_pk_add_f32 v[6:7], v[6:7], v[22:23] neg_lo:[0,1] neg_hi:[0,1]
	s_nop 0
	v_pk_mul_f32 v[22:23], v[6:7], s[34:35]
	s_nop 0
	v_pk_fma_f32 v[6:7], v[6:7], s[26:27], v[22:23] op_sel:[0,0,1] op_sel_hi:[1,0,0]
	v_pk_add_f32 v[22:23], v[8:9], v[26:27]
	v_pk_add_f32 v[8:9], v[8:9], v[26:27] neg_lo:[0,1] neg_hi:[0,1]
	v_pk_add_f32 v[26:27], v[10:11], v[28:29]
	v_pk_add_f32 v[10:11], v[10:11], v[28:29] neg_lo:[0,1] neg_hi:[0,1]
	s_nop 0
	v_pk_mul_f32 v[28:29], v[10:11], s[34:35]
	s_nop 0
	v_pk_fma_f32 v[10:11], v[10:11], s[26:27], v[28:29] op_sel:[0,0,1] op_sel_hi:[1,0,0] neg_lo:[1,0,0] neg_hi:[1,0,0]
	v_pk_add_f32 v[28:29], v[12:13], v[30:31]
	v_pk_add_f32 v[12:13], v[12:13], v[30:31] neg_lo:[0,1] neg_hi:[0,1]
	s_nop 0
	v_pk_mul_f32 v[30:31], v[12:13], s[10:11]
	s_nop 0
	v_pk_fma_f32 v[12:13], v[12:13], s[14:15], v[30:31] op_sel:[0,0,1] op_sel_hi:[1,0,0] neg_lo:[1,0,0] neg_hi:[1,0,0]
	v_pk_add_f32 v[30:31], v[14:15], v[24:25]
	v_pk_add_f32 v[14:15], v[14:15], v[24:25] neg_lo:[0,1] neg_hi:[0,1]
	s_nop 0
	v_pk_mul_f32 v[24:25], v[14:15], s[18:19]
	s_nop 0
	v_pk_fma_f32 v[14:15], v[14:15], s[30:31], v[24:25] op_sel:[0,0,1] op_sel_hi:[1,0,0] neg_lo:[1,0,0] neg_hi:[1,0,0]
	v_pk_add_f32 v[24:25], v[86:87], v[22:23]
	v_pk_add_f32 v[22:23], v[86:87], v[22:23] neg_lo:[0,1] neg_hi:[0,1]
	v_pk_add_f32 v[86:87], v[16:17], v[26:27]
	v_pk_add_f32 v[16:17], v[16:17], v[26:27] neg_lo:[0,1] neg_hi:[0,1]
	s_nop 0
	v_pk_mul_f32 v[26:27], v[16:17], s[10:11]
	s_nop 0
	v_pk_fma_f32 v[16:17], v[16:17], s[14:15], v[26:27] op_sel:[0,0,1] op_sel_hi:[1,0,0]
	v_pk_add_f32 v[26:27], v[18:19], v[28:29]
	v_pk_add_f32 v[18:19], v[18:19], v[28:29] neg_lo:[0,1] neg_hi:[0,1]
	v_pk_add_f32 v[28:29], v[20:21], v[30:31]
	v_pk_add_f32 v[20:21], v[20:21], v[30:31] neg_lo:[0,1] neg_hi:[0,1]
	s_nop 0
	v_pk_mul_f32 v[30:31], v[20:21], s[10:11]
	s_nop 0
	v_pk_fma_f32 v[20:21], v[20:21], s[14:15], v[30:31] op_sel:[0,0,1] op_sel_hi:[1,0,0] neg_lo:[1,0,0] neg_hi:[1,0,0]
	v_pk_add_f32 v[30:31], v[0:1], v[8:9] op_sel:[0,1] op_sel_hi:[1,0] neg_hi:[0,1]
	v_pk_add_f32 v[0:1], v[0:1], v[8:9] op_sel:[0,1] op_sel_hi:[1,0] neg_lo:[0,1]
	v_pk_add_f32 v[8:9], v[2:3], v[10:11]
	v_pk_add_f32 v[2:3], v[2:3], v[10:11] neg_lo:[0,1] neg_hi:[0,1]
	s_nop 0
	v_pk_mul_f32 v[10:11], v[2:3], s[10:11]
	s_nop 0
	v_pk_fma_f32 v[2:3], v[2:3], s[14:15], v[10:11] op_sel:[0,0,1] op_sel_hi:[1,0,0]
	v_pk_add_f32 v[10:11], v[4:5], v[12:13]
	v_pk_add_f32 v[4:5], v[4:5], v[12:13] neg_lo:[0,1] neg_hi:[0,1]
	v_pk_add_f32 v[12:13], v[6:7], v[14:15]
	v_pk_add_f32 v[6:7], v[6:7], v[14:15] neg_lo:[0,1] neg_hi:[0,1]
	s_nop 0
	v_pk_mul_f32 v[14:15], v[6:7], s[10:11]
	s_nop 0
	v_pk_fma_f32 v[6:7], v[6:7], s[14:15], v[14:15] op_sel:[0,0,1] op_sel_hi:[1,0,0] neg_lo:[1,0,0] neg_hi:[1,0,0]
	v_pk_add_f32 v[14:15], v[24:25], v[26:27]
	v_pk_add_f32 v[24:25], v[24:25], v[26:27] neg_lo:[0,1] neg_hi:[0,1]
	v_pk_add_f32 v[26:27], v[86:87], v[28:29]
	v_pk_add_f32 v[28:29], v[86:87], v[28:29] neg_lo:[0,1] neg_hi:[0,1]
	v_pk_add_f32 v[86:87], v[22:23], v[18:19] op_sel:[0,1] op_sel_hi:[1,0] neg_hi:[0,1]
	v_pk_add_f32 v[18:19], v[22:23], v[18:19] op_sel:[0,1] op_sel_hi:[1,0] neg_lo:[0,1]
	v_pk_add_f32 v[22:23], v[16:17], v[20:21]
	v_pk_add_f32 v[16:17], v[16:17], v[20:21] neg_lo:[0,1] neg_hi:[0,1]
	v_pk_add_f32 v[20:21], v[30:31], v[10:11]
	v_pk_add_f32 v[10:11], v[30:31], v[10:11] neg_lo:[0,1] neg_hi:[0,1]
	v_pk_add_f32 v[30:31], v[8:9], v[12:13]
	v_pk_add_f32 v[8:9], v[8:9], v[12:13] neg_lo:[0,1] neg_hi:[0,1]
	v_pk_add_f32 v[12:13], v[0:1], v[4:5] op_sel:[0,1] op_sel_hi:[1,0] neg_hi:[0,1]
	v_pk_add_f32 v[0:1], v[0:1], v[4:5] op_sel:[0,1] op_sel_hi:[1,0] neg_lo:[0,1]
	v_pk_add_f32 v[4:5], v[2:3], v[6:7]
	v_pk_add_f32 v[2:3], v[2:3], v[6:7] neg_lo:[0,1] neg_hi:[0,1]
	s_nop 0
	v_pk_mul_f32 v[2:3], v[2:3], s[22:23]
	v_pk_add_f32 v[6:7], v[14:15], v[26:27]
	v_pk_add_f32 v[14:15], v[14:15], v[26:27] neg_lo:[0,1] neg_hi:[0,1]
	v_pk_add_f32 v[26:27], v[24:25], v[28:29] op_sel:[0,1] op_sel_hi:[1,0] neg_hi:[0,1]
	v_pk_add_f32 v[24:25], v[24:25], v[28:29] op_sel:[0,1] op_sel_hi:[1,0] neg_lo:[0,1]
	v_pk_add_f32 v[28:29], v[86:87], v[22:23]
	v_pk_add_f32 v[22:23], v[86:87], v[22:23] neg_lo:[0,1] neg_hi:[0,1]
	v_pk_add_f32 v[86:87], v[18:19], v[16:17] op_sel:[0,1] op_sel_hi:[1,0] neg_hi:[0,1]
	v_pk_add_f32 v[16:17], v[18:19], v[16:17] op_sel:[0,1] op_sel_hi:[1,0] neg_lo:[0,1]
	v_pk_add_f32 v[18:19], v[20:21], v[30:31]
	v_pk_add_f32 v[20:21], v[20:21], v[30:31] neg_lo:[0,1] neg_hi:[0,1]
	v_pk_add_f32 v[30:31], v[10:11], v[8:9] op_sel:[0,1] op_sel_hi:[1,0] neg_hi:[0,1]
	v_pk_add_f32 v[8:9], v[10:11], v[8:9] op_sel:[0,1] op_sel_hi:[1,0] neg_lo:[0,1]
	v_pk_add_f32 v[10:11], v[12:13], v[4:5]
	v_pk_add_f32 v[4:5], v[12:13], v[4:5] neg_lo:[0,1] neg_hi:[0,1]
	v_pk_add_f32 v[12:13], v[0:1], v[2:3] op_sel:[0,1] op_sel_hi:[1,0]
	v_pk_add_f32 v[0:1], v[0:1], v[2:3] op_sel:[0,1] op_sel_hi:[1,0] neg_lo:[0,1] neg_hi:[0,1]
	v_lshlrev_b32_e32 v2, 4, v41
	v_and_or_b32 v2, v2, s7, v98
	v_ashrrev_i32_e32 v3, 4, v2
	v_lshlrev_b32_e32 v3, 3, v3
	v_lshlrev_b32_e32 v2, 3, v2
	v_add3_u32 v2, 0, v3, v2
	v_add_u32_e32 v3, 0x800, v2
	v_mov_b32_e32 v41, v32
	ds_write2_b64 v2, v[6:7], v[18:19] offset1:34
	ds_write2_b64 v3, v[14:15], v[20:21] offset0:16 offset1:50
	ds_write2_b64 v2, v[26:27], v[30:31] offset0:136 offset1:170
	ds_write2_b64 v3, v[24:25], v[8:9] offset0:152 offset1:186
	ds_write2_b64 v2, v[28:29], v[10:11] offset0:68 offset1:102
	ds_write2_b64 v3, v[22:23], v[4:5] offset0:84 offset1:118
	ds_write2_b64 v2, v[86:87], v[12:13] offset0:204 offset1:238
	ds_write2_b64 v3, v[16:17], v[0:1] offset0:220 offset1:254
	s_waitcnt lgkmcnt(0)
	s_barrier
	s_add_u32 s100, s38, 0x400000
	s_addc_u32 s101, s39, 0
	v_lshl_add_u64 v[224:225], v[48:49], 1, s[100:101]
	global_load_dword v226, v[224:225], off
	s_add_u32 s100, s38, 0x1000000
	s_addc_u32 s101, s39, 0
	v_lshl_add_u64 v[228:229], v[48:49], 1, s[100:101]
	global_load_dword v226, v[228:229], off
	s_nop 0
	v_and_b32_e32 v98, 0x1ff, v41
	v_cvt_f32_u32_e32 v24, v98
	v_ashrrev_i32_e32 v0, 4, v41
	v_lshlrev_b32_e32 v0, 3, v0
	v_lshlrev_b32_e32 v1, 3, v41
	v_mul_f32_e32 v92, 0x39000000, v24
	v_sin_f32_e32 v24, v92
	v_cos_f32_e32 v92, v92
	v_add3_u32 v25, 0, v0, v1
	ds_read_b64 v[0:1], v25
	ds_read_b64 v[2:3], v25 offset:4352
	ds_read_b64 v[4:5], v25 offset:8704
	ds_read_b64 v[6:7], v25 offset:13056
	ds_read_b64 v[8:9], v25 offset:17408
	ds_read_b64 v[10:11], v25 offset:21760
	ds_read_b64 v[12:13], v25 offset:26112
	ds_read_b64 v[14:15], v25 offset:30464
	v_xor_b32_e32 v93, 0x80000000, v24
	s_waitcnt lgkmcnt(6)
	v_pk_mul_f32 v[94:95], v[2:3], v[24:25] op_sel:[1,0] op_sel_hi:[0,0] neg_hi:[0,1]
	v_pk_fma_f32 v[2:3], v[2:3], v[92:93], v[94:95] op_sel_hi:[1,0,1]
	v_pk_mul_f32 v[94:95], v[24:25], v[92:93] op_sel:[0,1] op_sel_hi:[0,0] neg_hi:[1,0]
	v_pk_fma_f32 v[94:95], v[92:93], v[92:93], v[94:95] op_sel_hi:[0,1,1]
	ds_read_b64 v[16:17], v25 offset:34816
	ds_read_b64 v[18:19], v25 offset:39168
	ds_read_b64 v[20:21], v25 offset:43520
	ds_read_b64 v[22:23], v25 offset:47872
	s_waitcnt lgkmcnt(9)
	v_pk_mul_f32 v[96:97], v[4:5], v[94:95] op_sel:[1,1] op_sel_hi:[0,1] neg_lo:[0,1]
	v_pk_fma_f32 v[4:5], v[4:5], v[94:95], v[96:97] op_sel_hi:[1,0,1]
	v_pk_mul_f32 v[96:97], v[24:25], v[94:95] op_sel:[0,1] op_sel_hi:[0,0] neg_hi:[1,0]
	v_pk_fma_f32 v[94:95], v[92:93], v[94:95], v[96:97] op_sel_hi:[0,1,1]
	ds_read_b64 v[26:27], v25 offset:52224
	ds_read_b64 v[28:29], v25 offset:56576
	ds_read_b64 v[30:31], v25 offset:60928
	ds_read_b64 v[86:87], v25 offset:65280
	s_waitcnt lgkmcnt(12)
	v_pk_mul_f32 v[96:97], v[6:7], v[94:95] op_sel:[1,1] op_sel_hi:[0,1] neg_lo:[0,1]
	v_pk_fma_f32 v[6:7], v[6:7], v[94:95], v[96:97] op_sel_hi:[1,0,1]
	v_pk_mul_f32 v[96:97], v[24:25], v[94:95] op_sel:[0,1] op_sel_hi:[0,0] neg_hi:[1,0]
	v_pk_fma_f32 v[94:95], v[92:93], v[94:95], v[96:97] op_sel_hi:[0,1,1]
	s_waitcnt lgkmcnt(0)
	v_pk_mul_f32 v[96:97], v[8:9], v[94:95] op_sel:[1,1] op_sel_hi:[0,1] neg_lo:[0,1]
	v_pk_fma_f32 v[8:9], v[8:9], v[94:95], v[96:97] op_sel_hi:[1,0,1]
	v_pk_mul_f32 v[96:97], v[24:25], v[94:95] op_sel:[0,1] op_sel_hi:[0,0] neg_hi:[1,0]
	v_pk_fma_f32 v[94:95], v[92:93], v[94:95], v[96:97] op_sel_hi:[0,1,1]
	s_barrier
	v_pk_mul_f32 v[96:97], v[10:11], v[94:95] op_sel:[1,1] op_sel_hi:[0,1] neg_lo:[0,1]
	v_pk_fma_f32 v[10:11], v[10:11], v[94:95], v[96:97] op_sel_hi:[1,0,1]
	v_pk_mul_f32 v[96:97], v[24:25], v[94:95] op_sel:[0,1] op_sel_hi:[0,0] neg_hi:[1,0]
	v_pk_fma_f32 v[94:95], v[92:93], v[94:95], v[96:97] op_sel_hi:[0,1,1]
	s_nop 0
	v_pk_mul_f32 v[96:97], v[12:13], v[94:95] op_sel:[1,1] op_sel_hi:[0,1] neg_lo:[0,1]
	v_pk_fma_f32 v[12:13], v[12:13], v[94:95], v[96:97] op_sel_hi:[1,0,1]
	v_pk_mul_f32 v[96:97], v[24:25], v[94:95] op_sel:[0,1] op_sel_hi:[0,0] neg_hi:[1,0]
	v_pk_fma_f32 v[94:95], v[92:93], v[94:95], v[96:97] op_sel_hi:[0,1,1]
	s_nop 0
	v_pk_mul_f32 v[96:97], v[14:15], v[94:95] op_sel:[1,1] op_sel_hi:[0,1] neg_lo:[0,1]
	v_pk_fma_f32 v[14:15], v[14:15], v[94:95], v[96:97] op_sel_hi:[1,0,1]
	v_pk_mul_f32 v[96:97], v[24:25], v[94:95] op_sel:[0,1] op_sel_hi:[0,0] neg_hi:[1,0]
	v_pk_fma_f32 v[94:95], v[92:93], v[94:95], v[96:97] op_sel_hi:[0,1,1]
	s_nop 0
	v_pk_mul_f32 v[96:97], v[16:17], v[94:95] op_sel:[1,1] op_sel_hi:[0,1] neg_lo:[0,1]
	v_pk_fma_f32 v[16:17], v[16:17], v[94:95], v[96:97] op_sel_hi:[1,0,1]
	v_pk_mul_f32 v[96:97], v[24:25], v[94:95] op_sel:[0,1] op_sel_hi:[0,0] neg_hi:[1,0]
	v_pk_fma_f32 v[94:95], v[92:93], v[94:95], v[96:97] op_sel_hi:[0,1,1]
	s_nop 0
	v_pk_mul_f32 v[96:97], v[18:19], v[94:95] op_sel:[1,1] op_sel_hi:[0,1] neg_lo:[0,1]
	v_pk_fma_f32 v[18:19], v[18:19], v[94:95], v[96:97] op_sel_hi:[1,0,1]
	v_pk_mul_f32 v[96:97], v[24:25], v[94:95] op_sel:[0,1] op_sel_hi:[0,0] neg_hi:[1,0]
	v_pk_fma_f32 v[94:95], v[92:93], v[94:95], v[96:97] op_sel_hi:[0,1,1]
	s_nop 0
	v_pk_mul_f32 v[96:97], v[20:21], v[94:95] op_sel:[1,1] op_sel_hi:[0,1] neg_lo:[0,1]
	v_pk_fma_f32 v[20:21], v[20:21], v[94:95], v[96:97] op_sel_hi:[1,0,1]
	v_pk_mul_f32 v[96:97], v[24:25], v[94:95] op_sel:[0,1] op_sel_hi:[0,0] neg_hi:[1,0]
	v_pk_fma_f32 v[94:95], v[92:93], v[94:95], v[96:97] op_sel_hi:[0,1,1]
	s_nop 0
	v_pk_mul_f32 v[96:97], v[22:23], v[94:95] op_sel:[1,1] op_sel_hi:[0,1] neg_lo:[0,1]
	v_pk_fma_f32 v[22:23], v[22:23], v[94:95], v[96:97] op_sel_hi:[1,0,1]
	v_pk_mul_f32 v[96:97], v[24:25], v[94:95] op_sel:[0,1] op_sel_hi:[0,0] neg_hi:[1,0]
	v_pk_fma_f32 v[94:95], v[92:93], v[94:95], v[96:97] op_sel_hi:[0,1,1]
	s_nop 0
	v_pk_mul_f32 v[96:97], v[26:27], v[94:95] op_sel:[1,1] op_sel_hi:[0,1] neg_lo:[0,1]
	v_pk_fma_f32 v[26:27], v[26:27], v[94:95], v[96:97] op_sel_hi:[1,0,1]
	v_pk_mul_f32 v[96:97], v[24:25], v[94:95] op_sel:[0,1] op_sel_hi:[0,0] neg_hi:[1,0]
	v_pk_fma_f32 v[94:95], v[92:93], v[94:95], v[96:97] op_sel_hi:[0,1,1]
	s_nop 0
	v_pk_mul_f32 v[96:97], v[28:29], v[94:95] op_sel:[1,1] op_sel_hi:[0,1] neg_lo:[0,1]
	v_pk_fma_f32 v[28:29], v[28:29], v[94:95], v[96:97] op_sel_hi:[1,0,1]
	v_pk_mul_f32 v[96:97], v[24:25], v[94:95] op_sel:[0,1] op_sel_hi:[0,0] neg_hi:[1,0]
	v_pk_fma_f32 v[94:95], v[92:93], v[94:95], v[96:97] op_sel_hi:[0,1,1]
	v_pk_mul_f32 v[24:25], v[24:25], v[94:95] op_sel:[0,1] op_sel_hi:[0,0] neg_hi:[1,0]
	v_pk_fma_f32 v[24:25], v[92:93], v[94:95], v[24:25] op_sel_hi:[0,1,1]
	v_pk_mul_f32 v[92:93], v[86:87], v[24:25] op_sel:[1,1] op_sel_hi:[0,1] neg_lo:[0,1]
	v_pk_fma_f32 v[24:25], v[86:87], v[24:25], v[92:93] op_sel_hi:[1,0,1]
	v_pk_add_f32 v[86:87], v[0:1], v[16:17]
	v_pk_add_f32 v[0:1], v[0:1], v[16:17] neg_lo:[0,1] neg_hi:[0,1]
	v_pk_add_f32 v[16:17], v[2:3], v[18:19]
	v_pk_add_f32 v[2:3], v[2:3], v[18:19] neg_lo:[0,1] neg_hi:[0,1]
	v_pk_mul_f32 v[96:97], v[30:31], v[94:95] op_sel:[1,1] op_sel_hi:[0,1] neg_lo:[0,1]
	v_pk_mul_f32 v[18:19], v[2:3], s[18:19]
	v_pk_fma_f32 v[30:31], v[30:31], v[94:95], v[96:97] op_sel_hi:[1,0,1]
	v_pk_fma_f32 v[2:3], v[2:3], s[30:31], v[18:19] op_sel:[0,0,1] op_sel_hi:[1,0,0]
	v_pk_add_f32 v[18:19], v[4:5], v[20:21]
	v_pk_add_f32 v[4:5], v[4:5], v[20:21] neg_lo:[0,1] neg_hi:[0,1]
	s_nop 0
	v_pk_mul_f32 v[20:21], v[4:5], s[10:11]
	s_nop 0
	v_pk_fma_f32 v[4:5], v[4:5], s[14:15], v[20:21] op_sel:[0,0,1] op_sel_hi:[1,0,0]
	v_pk_add_f32 v[20:21], v[6:7], v[22:23]
	v_pk_add_f32 v[6:7], v[6:7], v[22:23] neg_lo:[0,1] neg_hi:[0,1]
	s_nop 0
	v_pk_mul_f32 v[22:23], v[6:7], s[34:35]
	s_nop 0
	v_pk_fma_f32 v[6:7], v[6:7], s[26:27], v[22:23] op_sel:[0,0,1] op_sel_hi:[1,0,0]
	v_pk_add_f32 v[22:23], v[8:9], v[26:27]
	v_pk_add_f32 v[8:9], v[8:9], v[26:27] neg_lo:[0,1] neg_hi:[0,1]
	v_pk_add_f32 v[26:27], v[10:11], v[28:29]
	v_pk_add_f32 v[10:11], v[10:11], v[28:29] neg_lo:[0,1] neg_hi:[0,1]
	s_nop 0
	v_pk_mul_f32 v[28:29], v[10:11], s[34:35]
	s_nop 0
	v_pk_fma_f32 v[10:11], v[10:11], s[26:27], v[28:29] op_sel:[0,0,1] op_sel_hi:[1,0,0] neg_lo:[1,0,0] neg_hi:[1,0,0]
	v_pk_add_f32 v[28:29], v[12:13], v[30:31]
	v_pk_add_f32 v[12:13], v[12:13], v[30:31] neg_lo:[0,1] neg_hi:[0,1]
	s_nop 0
	v_pk_mul_f32 v[30:31], v[12:13], s[10:11]
	s_nop 0
	v_pk_fma_f32 v[12:13], v[12:13], s[14:15], v[30:31] op_sel:[0,0,1] op_sel_hi:[1,0,0] neg_lo:[1,0,0] neg_hi:[1,0,0]
	v_pk_add_f32 v[30:31], v[14:15], v[24:25]
	v_pk_add_f32 v[14:15], v[14:15], v[24:25] neg_lo:[0,1] neg_hi:[0,1]
	s_nop 0
	v_pk_mul_f32 v[24:25], v[14:15], s[18:19]
	s_nop 0
	v_pk_fma_f32 v[14:15], v[14:15], s[30:31], v[24:25] op_sel:[0,0,1] op_sel_hi:[1,0,0] neg_lo:[1,0,0] neg_hi:[1,0,0]
	v_pk_add_f32 v[24:25], v[86:87], v[22:23]
	v_pk_add_f32 v[22:23], v[86:87], v[22:23] neg_lo:[0,1] neg_hi:[0,1]
	v_pk_add_f32 v[86:87], v[16:17], v[26:27]
	v_pk_add_f32 v[16:17], v[16:17], v[26:27] neg_lo:[0,1] neg_hi:[0,1]
	s_nop 0
	v_pk_mul_f32 v[26:27], v[16:17], s[10:11]
	s_nop 0
	v_pk_fma_f32 v[16:17], v[16:17], s[14:15], v[26:27] op_sel:[0,0,1] op_sel_hi:[1,0,0]
	v_pk_add_f32 v[26:27], v[18:19], v[28:29]
	v_pk_add_f32 v[18:19], v[18:19], v[28:29] neg_lo:[0,1] neg_hi:[0,1]
	v_pk_add_f32 v[28:29], v[20:21], v[30:31]
	v_pk_add_f32 v[20:21], v[20:21], v[30:31] neg_lo:[0,1] neg_hi:[0,1]
	s_nop 0
	v_pk_mul_f32 v[30:31], v[20:21], s[10:11]
	s_nop 0
	v_pk_fma_f32 v[20:21], v[20:21], s[14:15], v[30:31] op_sel:[0,0,1] op_sel_hi:[1,0,0] neg_lo:[1,0,0] neg_hi:[1,0,0]
	v_pk_add_f32 v[30:31], v[0:1], v[8:9] op_sel:[0,1] op_sel_hi:[1,0] neg_hi:[0,1]
	v_pk_add_f32 v[0:1], v[0:1], v[8:9] op_sel:[0,1] op_sel_hi:[1,0] neg_lo:[0,1]
	v_pk_add_f32 v[8:9], v[2:3], v[10:11]
	v_pk_add_f32 v[2:3], v[2:3], v[10:11] neg_lo:[0,1] neg_hi:[0,1]
	s_nop 0
	v_pk_mul_f32 v[10:11], v[2:3], s[10:11]
	s_nop 0
	v_pk_fma_f32 v[2:3], v[2:3], s[14:15], v[10:11] op_sel:[0,0,1] op_sel_hi:[1,0,0]
	v_pk_add_f32 v[10:11], v[4:5], v[12:13]
	v_pk_add_f32 v[4:5], v[4:5], v[12:13] neg_lo:[0,1] neg_hi:[0,1]
	v_pk_add_f32 v[12:13], v[6:7], v[14:15]
	v_pk_add_f32 v[6:7], v[6:7], v[14:15] neg_lo:[0,1] neg_hi:[0,1]
	s_nop 0
	v_pk_mul_f32 v[14:15], v[6:7], s[10:11]
	s_nop 0
	v_pk_fma_f32 v[6:7], v[6:7], s[14:15], v[14:15] op_sel:[0,0,1] op_sel_hi:[1,0,0] neg_lo:[1,0,0] neg_hi:[1,0,0]
	v_pk_add_f32 v[14:15], v[24:25], v[26:27]
	v_pk_add_f32 v[24:25], v[24:25], v[26:27] neg_lo:[0,1] neg_hi:[0,1]
	v_pk_add_f32 v[26:27], v[86:87], v[28:29]
	v_pk_add_f32 v[28:29], v[86:87], v[28:29] neg_lo:[0,1] neg_hi:[0,1]
	v_pk_add_f32 v[86:87], v[22:23], v[18:19] op_sel:[0,1] op_sel_hi:[1,0] neg_hi:[0,1]
	v_pk_add_f32 v[18:19], v[22:23], v[18:19] op_sel:[0,1] op_sel_hi:[1,0] neg_lo:[0,1]
	v_pk_add_f32 v[22:23], v[16:17], v[20:21]
	v_pk_add_f32 v[16:17], v[16:17], v[20:21] neg_lo:[0,1] neg_hi:[0,1]
	v_pk_add_f32 v[20:21], v[30:31], v[10:11]
	v_pk_add_f32 v[10:11], v[30:31], v[10:11] neg_lo:[0,1] neg_hi:[0,1]
	v_pk_add_f32 v[30:31], v[8:9], v[12:13]
	v_pk_add_f32 v[8:9], v[8:9], v[12:13] neg_lo:[0,1] neg_hi:[0,1]
	v_pk_add_f32 v[12:13], v[0:1], v[4:5] op_sel:[0,1] op_sel_hi:[1,0] neg_hi:[0,1]
	v_pk_add_f32 v[0:1], v[0:1], v[4:5] op_sel:[0,1] op_sel_hi:[1,0] neg_lo:[0,1]
	v_pk_add_f32 v[4:5], v[2:3], v[6:7]
	v_pk_add_f32 v[2:3], v[2:3], v[6:7] neg_lo:[0,1] neg_hi:[0,1]
	s_nop 0
	v_pk_mul_f32 v[2:3], v[2:3], s[22:23]
	v_pk_add_f32 v[6:7], v[14:15], v[26:27]
	v_pk_add_f32 v[14:15], v[14:15], v[26:27] neg_lo:[0,1] neg_hi:[0,1]
	v_pk_add_f32 v[26:27], v[24:25], v[28:29] op_sel:[0,1] op_sel_hi:[1,0] neg_hi:[0,1]
	v_pk_add_f32 v[24:25], v[24:25], v[28:29] op_sel:[0,1] op_sel_hi:[1,0] neg_lo:[0,1]
	v_pk_add_f32 v[28:29], v[86:87], v[22:23]
	v_pk_add_f32 v[22:23], v[86:87], v[22:23] neg_lo:[0,1] neg_hi:[0,1]
	v_pk_add_f32 v[86:87], v[18:19], v[16:17] op_sel:[0,1] op_sel_hi:[1,0] neg_hi:[0,1]
	v_pk_add_f32 v[16:17], v[18:19], v[16:17] op_sel:[0,1] op_sel_hi:[1,0] neg_lo:[0,1]
	v_pk_add_f32 v[18:19], v[20:21], v[30:31]
	v_pk_add_f32 v[20:21], v[20:21], v[30:31] neg_lo:[0,1] neg_hi:[0,1]
	v_pk_add_f32 v[30:31], v[10:11], v[8:9] op_sel:[0,1] op_sel_hi:[1,0] neg_hi:[0,1]
	v_pk_add_f32 v[8:9], v[10:11], v[8:9] op_sel:[0,1] op_sel_hi:[1,0] neg_lo:[0,1]
	v_pk_add_f32 v[10:11], v[12:13], v[4:5]
	v_pk_add_f32 v[4:5], v[12:13], v[4:5] neg_lo:[0,1] neg_hi:[0,1]
	v_pk_add_f32 v[12:13], v[0:1], v[2:3] op_sel:[0,1] op_sel_hi:[1,0]
	v_pk_add_f32 v[0:1], v[0:1], v[2:3] op_sel:[0,1] op_sel_hi:[1,0] neg_lo:[0,1] neg_hi:[0,1]
	v_lshlrev_b32_e32 v2, 4, v41
	v_and_or_b32 v2, v2, s15, v98
	v_ashrrev_i32_e32 v3, 4, v2
	v_lshlrev_b32_e32 v3, 3, v3
	v_lshlrev_b32_e32 v2, 3, v2
	v_add3_u32 v2, 0, v3, v2
	ds_write_b64 v2, v[6:7]
	ds_write_b64 v2, v[14:15] offset:34816
	ds_write_b64 v2, v[26:27] offset:17408
	ds_write_b64 v2, v[24:25] offset:52224
	ds_write_b64 v2, v[28:29] offset:8704
	ds_write_b64 v2, v[22:23] offset:43520
	ds_write_b64 v2, v[86:87] offset:26112
	ds_write_b64 v2, v[16:17] offset:60928
	ds_write_b64 v2, v[18:19] offset:4352
	ds_write_b64 v2, v[20:21] offset:39168
	ds_write_b64 v2, v[30:31] offset:21760
	ds_write_b64 v2, v[8:9] offset:56576
	ds_write_b64 v2, v[10:11] offset:13056
	ds_write_b64 v2, v[4:5] offset:47872
	ds_write_b64 v2, v[12:13] offset:30464
	ds_write_b64 v2, v[0:1] offset:65280
	s_waitcnt lgkmcnt(0)
	s_barrier
	s_and_saveexec_b64 s[28:29], s[40:41]
	s_cbranch_execz .LBB0_633
	s_add_u32 s4, s38, 0x400000
	s_addc_u32 s5, s39, 0
	v_lshl_add_u64 v[0:1], v[48:49], 1, s[4:5]
	global_load_dwordx4 v[8:11], v[0:1], off offset:16
	global_load_dwordx4 v[12:15], v[0:1], off
	v_mov_b32_e32 v19, 0
	v_mov_b32_e32 v18, 0
	v_mov_b32_e32 v86, 0
	s_and_saveexec_b64 s[8:9], s[42:43]
	s_cbranch_execz .LBB0_626
	v_lshl_add_u64 v[2:3], v[172:173], 1, s[4:5]
	global_load_ushort v86, v[2:3], off offset:-2

.LBB0_675:
	s_or_b64 exec, exec, s[4:5]
	v_mov_b32_e32 v41, v32
	s_waitcnt lgkmcnt(0)
	s_barrier
	s_mov_b32 s11, s14
	v_and_b32_e32 v98, 31, v41
	v_cvt_f32_ubyte0_e32 v24, v98
	v_mul_f32_e32 v60, 0x3b000000, v24
	v_sin_f32_e32 v24, v60
	v_ashrrev_i32_e32 v0, 4, v41
	v_lshlrev_b32_e32 v0, 3, v0
	v_lshlrev_b32_e32 v1, 3, v41
	v_cos_f32_e32 v60, v60
	v_add3_u32 v25, 0, v0, v1
	ds_read_b64 v[0:1], v25
	ds_read_b64 v[2:3], v25 offset:4352
	ds_read_b64 v[4:5], v25 offset:8704
	ds_read_b64 v[6:7], v25 offset:13056
	ds_read_b64 v[8:9], v25 offset:17408
	ds_read_b64 v[10:11], v25 offset:21760
	ds_read_b64 v[12:13], v25 offset:26112
	ds_read_b64 v[14:15], v25 offset:30464
	ds_read_b64 v[16:17], v25 offset:34816
	ds_read_b64 v[18:19], v25 offset:39168
	ds_read_b64 v[20:21], v25 offset:43520
	ds_read_b64 v[22:23], v25 offset:47872
	v_xor_b32_e32 v61, 0x80000000, v24
	s_waitcnt lgkmcnt(10)
	v_pk_mul_f32 v[94:95], v[2:3], v[24:25] op_sel:[1,0] op_sel_hi:[0,0] neg_hi:[0,1]
	v_pk_fma_f32 v[2:3], v[2:3], v[60:61], v[94:95] op_sel_hi:[1,0,1]
	v_pk_mul_f32 v[94:95], v[24:25], v[60:61] op_sel:[0,1] op_sel_hi:[0,0] neg_hi:[1,0]
	v_pk_fma_f32 v[94:95], v[60:61], v[60:61], v[94:95] op_sel_hi:[0,1,1]
	ds_read_b64 v[26:27], v25 offset:52224
	ds_read_b64 v[28:29], v25 offset:56576
	ds_read_b64 v[30:31], v25 offset:60928
	ds_read_b64 v[58:59], v25 offset:65280
	s_waitcnt lgkmcnt(13)
	v_pk_mul_f32 v[96:97], v[4:5], v[94:95] op_sel:[1,1] op_sel_hi:[0,1] neg_lo:[0,1]
	v_pk_fma_f32 v[4:5], v[4:5], v[94:95], v[96:97] op_sel_hi:[1,0,1]
	v_pk_mul_f32 v[96:97], v[24:25], v[94:95] op_sel:[0,1] op_sel_hi:[0,0] neg_hi:[1,0]
	v_pk_fma_f32 v[94:95], v[60:61], v[94:95], v[96:97] op_sel_hi:[0,1,1]
	s_mov_b32 s35, s30
	s_waitcnt lgkmcnt(12)
	v_pk_mul_f32 v[96:97], v[6:7], v[94:95] op_sel:[1,1] op_sel_hi:[0,1] neg_lo:[0,1]
	v_pk_fma_f32 v[6:7], v[6:7], v[94:95], v[96:97] op_sel_hi:[1,0,1]
	v_pk_mul_f32 v[96:97], v[24:25], v[94:95] op_sel:[0,1] op_sel_hi:[0,0] neg_hi:[1,0]
	v_pk_fma_f32 v[94:95], v[60:61], v[94:95], v[96:97] op_sel_hi:[0,1,1]
	s_mov_b32 s26, s19
	s_waitcnt lgkmcnt(11)
	v_pk_mul_f32 v[96:97], v[8:9], v[94:95] op_sel:[1,1] op_sel_hi:[0,1] neg_lo:[0,1]
	v_pk_fma_f32 v[8:9], v[8:9], v[94:95], v[96:97] op_sel_hi:[1,0,1]
	v_pk_mul_f32 v[96:97], v[24:25], v[94:95] op_sel:[0,1] op_sel_hi:[0,0] neg_hi:[1,0]
	v_pk_fma_f32 v[94:95], v[60:61], v[94:95], v[96:97] op_sel_hi:[0,1,1]
	s_waitcnt lgkmcnt(0)
	v_pk_mul_f32 v[96:97], v[10:11], v[94:95] op_sel:[1,1] op_sel_hi:[0,1] neg_lo:[0,1]
	v_pk_fma_f32 v[10:11], v[10:11], v[94:95], v[96:97] op_sel_hi:[1,0,1]
	v_pk_mul_f32 v[96:97], v[24:25], v[94:95] op_sel:[0,1] op_sel_hi:[0,0] neg_hi:[1,0]
	v_pk_fma_f32 v[94:95], v[60:61], v[94:95], v[96:97] op_sel_hi:[0,1,1]
	s_barrier
	v_pk_mul_f32 v[96:97], v[12:13], v[94:95] op_sel:[1,1] op_sel_hi:[0,1] neg_lo:[0,1]
	v_pk_fma_f32 v[12:13], v[12:13], v[94:95], v[96:97] op_sel_hi:[1,0,1]
	v_pk_mul_f32 v[96:97], v[24:25], v[94:95] op_sel:[0,1] op_sel_hi:[0,0] neg_hi:[1,0]
	v_pk_fma_f32 v[94:95], v[60:61], v[94:95], v[96:97] op_sel_hi:[0,1,1]
	s_nop 0
	v_pk_mul_f32 v[96:97], v[14:15], v[94:95] op_sel:[1,1] op_sel_hi:[0,1] neg_lo:[0,1]
	v_pk_fma_f32 v[14:15], v[14:15], v[94:95], v[96:97] op_sel_hi:[1,0,1]
	v_pk_mul_f32 v[96:97], v[24:25], v[94:95] op_sel:[0,1] op_sel_hi:[0,0] neg_hi:[1,0]
	v_pk_fma_f32 v[94:95], v[60:61], v[94:95], v[96:97] op_sel_hi:[0,1,1]
	s_nop 0
	v_pk_mul_f32 v[96:97], v[16:17], v[94:95] op_sel:[1,1] op_sel_hi:[0,1] neg_lo:[0,1]
	v_pk_fma_f32 v[16:17], v[16:17], v[94:95], v[96:97] op_sel_hi:[1,0,1]
	v_pk_mul_f32 v[96:97], v[24:25], v[94:95] op_sel:[0,1] op_sel_hi:[0,0] neg_hi:[1,0]
	v_pk_fma_f32 v[94:95], v[60:61], v[94:95], v[96:97] op_sel_hi:[0,1,1]
	s_nop 0
	v_pk_mul_f32 v[96:97], v[18:19], v[94:95] op_sel:[1,1] op_sel_hi:[0,1] neg_lo:[0,1]
	v_pk_fma_f32 v[18:19], v[18:19], v[94:95], v[96:97] op_sel_hi:[1,0,1]
	v_pk_mul_f32 v[96:97], v[24:25], v[94:95] op_sel:[0,1] op_sel_hi:[0,0] neg_hi:[1,0]
	v_pk_fma_f32 v[94:95], v[60:61], v[94:95], v[96:97] op_sel_hi:[0,1,1]
	s_nop 0
	v_pk_mul_f32 v[96:97], v[20:21], v[94:95] op_sel:[1,1] op_sel_hi:[0,1] neg_lo:[0,1]
	v_pk_fma_f32 v[20:21], v[20:21], v[94:95], v[96:97] op_sel_hi:[1,0,1]
	v_pk_mul_f32 v[96:97], v[24:25], v[94:95] op_sel:[0,1] op_sel_hi:[0,0] neg_hi:[1,0]
	v_pk_fma_f32 v[94:95], v[60:61], v[94:95], v[96:97] op_sel_hi:[0,1,1]
	s_nop 0
	v_pk_mul_f32 v[96:97], v[22:23], v[94:95] op_sel:[1,1] op_sel_hi:[0,1] neg_lo:[0,1]
	v_pk_fma_f32 v[22:23], v[22:23], v[94:95], v[96:97] op_sel_hi:[1,0,1]
	v_pk_mul_f32 v[96:97], v[24:25], v[94:95] op_sel:[0,1] op_sel_hi:[0,0] neg_hi:[1,0]
	v_pk_fma_f32 v[94:95], v[60:61], v[94:95], v[96:97] op_sel_hi:[0,1,1]
	s_nop 0
	v_pk_mul_f32 v[96:97], v[26:27], v[94:95] op_sel:[1,1] op_sel_hi:[0,1] neg_lo:[0,1]
	v_pk_fma_f32 v[26:27], v[26:27], v[94:95], v[96:97] op_sel_hi:[1,0,1]
	v_pk_mul_f32 v[96:97], v[24:25], v[94:95] op_sel:[0,1] op_sel_hi:[0,0] neg_hi:[1,0]
	v_pk_fma_f32 v[94:95], v[60:61], v[94:95], v[96:97] op_sel_hi:[0,1,1]
	s_nop 0
	v_pk_mul_f32 v[96:97], v[28:29], v[94:95] op_sel:[1,1] op_sel_hi:[0,1] neg_lo:[0,1]
	v_pk_fma_f32 v[28:29], v[28:29], v[94:95], v[96:97] op_sel_hi:[1,0,1]
	v_pk_mul_f32 v[96:97], v[24:25], v[94:95] op_sel:[0,1] op_sel_hi:[0,0] neg_hi:[1,0]
	v_pk_fma_f32 v[94:95], v[60:61], v[94:95], v[96:97] op_sel_hi:[0,1,1]
	v_pk_mul_f32 v[24:25], v[24:25], v[94:95] op_sel:[0,1] op_sel_hi:[0,0] neg_hi:[1,0]
	v_pk_fma_f32 v[24:25], v[60:61], v[94:95], v[24:25] op_sel_hi:[0,1,1]
	v_pk_mul_f32 v[60:61], v[58:59], v[24:25] op_sel:[1,1] op_sel_hi:[0,1] neg_lo:[0,1]
	v_pk_fma_f32 v[24:25], v[58:59], v[24:25], v[60:61] op_sel_hi:[1,0,1]
	v_pk_add_f32 v[58:59], v[0:1], v[16:17]
	v_pk_add_f32 v[0:1], v[0:1], v[16:17] neg_lo:[0,1] neg_hi:[0,1]
	v_pk_add_f32 v[16:17], v[2:3], v[18:19]
	v_pk_add_f32 v[2:3], v[2:3], v[18:19] neg_lo:[0,1] neg_hi:[0,1]
	v_pk_mul_f32 v[96:97], v[30:31], v[94:95] op_sel:[1,1] op_sel_hi:[0,1] neg_lo:[0,1]
	v_pk_mul_f32 v[18:19], v[2:3], s[18:19]
	v_pk_fma_f32 v[30:31], v[30:31], v[94:95], v[96:97] op_sel_hi:[1,0,1]
	v_pk_fma_f32 v[2:3], v[2:3], s[30:31], v[18:19] op_sel:[0,0,1] op_sel_hi:[1,0,0]
	v_pk_add_f32 v[18:19], v[4:5], v[20:21]
	v_pk_add_f32 v[4:5], v[4:5], v[20:21] neg_lo:[0,1] neg_hi:[0,1]
	s_nop 0
	v_pk_mul_f32 v[20:21], v[4:5], s[10:11]
	s_nop 0
	v_pk_fma_f32 v[4:5], v[4:5], s[14:15], v[20:21] op_sel:[0,0,1] op_sel_hi:[1,0,0]
	v_pk_add_f32 v[20:21], v[6:7], v[22:23]
	v_pk_add_f32 v[6:7], v[6:7], v[22:23] neg_lo:[0,1] neg_hi:[0,1]
	s_nop 0
	v_pk_mul_f32 v[22:23], v[6:7], s[34:35]
	s_nop 0
	v_pk_fma_f32 v[6:7], v[6:7], s[26:27], v[22:23] op_sel:[0,0,1] op_sel_hi:[1,0,0]
	v_pk_add_f32 v[22:23], v[8:9], v[26:27]
	v_pk_add_f32 v[8:9], v[8:9], v[26:27] neg_lo:[0,1] neg_hi:[0,1]
	v_pk_add_f32 v[26:27], v[10:11], v[28:29]
	v_pk_add_f32 v[10:11], v[10:11], v[28:29] neg_lo:[0,1] neg_hi:[0,1]
	s_nop 0
	v_pk_mul_f32 v[28:29], v[10:11], s[34:35]
	s_nop 0
	v_pk_fma_f32 v[10:11], v[10:11], s[26:27], v[28:29] op_sel:[0,0,1] op_sel_hi:[1,0,0] neg_lo:[1,0,0] neg_hi:[1,0,0]
	v_pk_add_f32 v[28:29], v[12:13], v[30:31]
	v_pk_add_f32 v[12:13], v[12:13], v[30:31] neg_lo:[0,1] neg_hi:[0,1]
	s_nop 0
	v_pk_mul_f32 v[30:31], v[12:13], s[10:11]
	s_nop 0
	v_pk_fma_f32 v[12:13], v[12:13], s[14:15], v[30:31] op_sel:[0,0,1] op_sel_hi:[1,0,0] neg_lo:[1,0,0] neg_hi:[1,0,0]
	v_pk_add_f32 v[30:31], v[14:15], v[24:25]
	v_pk_add_f32 v[14:15], v[14:15], v[24:25] neg_lo:[0,1] neg_hi:[0,1]
	s_nop 0
	v_pk_mul_f32 v[24:25], v[14:15], s[18:19]
	s_nop 0
	v_pk_fma_f32 v[14:15], v[14:15], s[30:31], v[24:25] op_sel:[0,0,1] op_sel_hi:[1,0,0] neg_lo:[1,0,0] neg_hi:[1,0,0]
	v_pk_add_f32 v[24:25], v[58:59], v[22:23]
	v_pk_add_f32 v[22:23], v[58:59], v[22:23] neg_lo:[0,1] neg_hi:[0,1]
	v_pk_add_f32 v[58:59], v[16:17], v[26:27]
	v_pk_add_f32 v[16:17], v[16:17], v[26:27] neg_lo:[0,1] neg_hi:[0,1]
	s_nop 0
	v_pk_mul_f32 v[26:27], v[16:17], s[10:11]
	s_nop 0
	v_pk_fma_f32 v[16:17], v[16:17], s[14:15], v[26:27] op_sel:[0,0,1] op_sel_hi:[1,0,0]
	v_pk_add_f32 v[26:27], v[18:19], v[28:29]
	v_pk_add_f32 v[18:19], v[18:19], v[28:29] neg_lo:[0,1] neg_hi:[0,1]
	v_pk_add_f32 v[28:29], v[20:21], v[30:31]
	v_pk_add_f32 v[20:21], v[20:21], v[30:31] neg_lo:[0,1] neg_hi:[0,1]
	s_nop 0
	v_pk_mul_f32 v[30:31], v[20:21], s[10:11]
	s_nop 0
	v_pk_fma_f32 v[20:21], v[20:21], s[14:15], v[30:31] op_sel:[0,0,1] op_sel_hi:[1,0,0] neg_lo:[1,0,0] neg_hi:[1,0,0]
	v_pk_add_f32 v[30:31], v[0:1], v[8:9] op_sel:[0,1] op_sel_hi:[1,0] neg_hi:[0,1]
	v_pk_add_f32 v[0:1], v[0:1], v[8:9] op_sel:[0,1] op_sel_hi:[1,0] neg_lo:[0,1]
	v_pk_add_f32 v[8:9], v[2:3], v[10:11]
	v_pk_add_f32 v[2:3], v[2:3], v[10:11] neg_lo:[0,1] neg_hi:[0,1]
	s_nop 0
	v_pk_mul_f32 v[10:11], v[2:3], s[10:11]
	s_nop 0
	v_pk_fma_f32 v[2:3], v[2:3], s[14:15], v[10:11] op_sel:[0,0,1] op_sel_hi:[1,0,0]
	v_pk_add_f32 v[10:11], v[4:5], v[12:13]
	v_pk_add_f32 v[4:5], v[4:5], v[12:13] neg_lo:[0,1] neg_hi:[0,1]
	v_pk_add_f32 v[12:13], v[6:7], v[14:15]
	v_pk_add_f32 v[6:7], v[6:7], v[14:15] neg_lo:[0,1] neg_hi:[0,1]
	s_nop 0
	v_pk_mul_f32 v[14:15], v[6:7], s[10:11]
	s_nop 0
	v_pk_fma_f32 v[6:7], v[6:7], s[14:15], v[14:15] op_sel:[0,0,1] op_sel_hi:[1,0,0] neg_lo:[1,0,0] neg_hi:[1,0,0]
	v_pk_add_f32 v[14:15], v[24:25], v[26:27]
	v_pk_add_f32 v[24:25], v[24:25], v[26:27] neg_lo:[0,1] neg_hi:[0,1]
	v_pk_add_f32 v[26:27], v[58:59], v[28:29]
	v_pk_add_f32 v[28:29], v[58:59], v[28:29] neg_lo:[0,1] neg_hi:[0,1]
	v_pk_add_f32 v[58:59], v[22:23], v[18:19] op_sel:[0,1] op_sel_hi:[1,0] neg_hi:[0,1]
	v_pk_add_f32 v[18:19], v[22:23], v[18:19] op_sel:[0,1] op_sel_hi:[1,0] neg_lo:[0,1]
	v_pk_add_f32 v[22:23], v[16:17], v[20:21]
	v_pk_add_f32 v[16:17], v[16:17], v[20:21] neg_lo:[0,1] neg_hi:[0,1]
	v_pk_add_f32 v[20:21], v[30:31], v[10:11]
	v_pk_add_f32 v[10:11], v[30:31], v[10:11] neg_lo:[0,1] neg_hi:[0,1]
	v_pk_add_f32 v[30:31], v[8:9], v[12:13]
	v_pk_add_f32 v[8:9], v[8:9], v[12:13] neg_lo:[0,1] neg_hi:[0,1]
	v_pk_add_f32 v[12:13], v[0:1], v[4:5] op_sel:[0,1] op_sel_hi:[1,0] neg_hi:[0,1]
	v_pk_add_f32 v[0:1], v[0:1], v[4:5] op_sel:[0,1] op_sel_hi:[1,0] neg_lo:[0,1]
	v_pk_add_f32 v[4:5], v[2:3], v[6:7]
	v_pk_add_f32 v[2:3], v[2:3], v[6:7] neg_lo:[0,1] neg_hi:[0,1]
	s_nop 0
	v_pk_mul_f32 v[2:3], v[2:3], s[22:23]
	v_pk_add_f32 v[6:7], v[14:15], v[26:27]
	v_pk_add_f32 v[14:15], v[14:15], v[26:27] neg_lo:[0,1] neg_hi:[0,1]
	v_pk_add_f32 v[26:27], v[24:25], v[28:29] op_sel:[0,1] op_sel_hi:[1,0] neg_hi:[0,1]
	v_pk_add_f32 v[24:25], v[24:25], v[28:29] op_sel:[0,1] op_sel_hi:[1,0] neg_lo:[0,1]
	v_pk_add_f32 v[28:29], v[58:59], v[22:23]
	v_pk_add_f32 v[22:23], v[58:59], v[22:23] neg_lo:[0,1] neg_hi:[0,1]
	v_pk_add_f32 v[58:59], v[18:19], v[16:17] op_sel:[0,1] op_sel_hi:[1,0] neg_hi:[0,1]
	v_pk_add_f32 v[16:17], v[18:19], v[16:17] op_sel:[0,1] op_sel_hi:[1,0] neg_lo:[0,1]
	v_pk_add_f32 v[18:19], v[20:21], v[30:31]
	v_pk_add_f32 v[20:21], v[20:21], v[30:31] neg_lo:[0,1] neg_hi:[0,1]
	v_pk_add_f32 v[30:31], v[10:11], v[8:9] op_sel:[0,1] op_sel_hi:[1,0] neg_hi:[0,1]
	v_pk_add_f32 v[8:9], v[10:11], v[8:9] op_sel:[0,1] op_sel_hi:[1,0] neg_lo:[0,1]
	v_pk_add_f32 v[10:11], v[12:13], v[4:5]
	v_pk_add_f32 v[4:5], v[12:13], v[4:5] neg_lo:[0,1] neg_hi:[0,1]
	v_pk_add_f32 v[12:13], v[0:1], v[2:3] op_sel:[0,1] op_sel_hi:[1,0]
	v_pk_add_f32 v[0:1], v[0:1], v[2:3] op_sel:[0,1] op_sel_hi:[1,0] neg_lo:[0,1] neg_hi:[0,1]
	v_lshlrev_b32_e32 v2, 4, v41
	v_and_or_b32 v2, v2, s7, v98
	v_ashrrev_i32_e32 v3, 4, v2
	v_lshlrev_b32_e32 v3, 3, v3
	v_lshlrev_b32_e32 v2, 3, v2
	v_add3_u32 v2, 0, v3, v2
	v_add_u32_e32 v3, 0x800, v2
	v_mov_b32_e32 v41, v32
	ds_write2_b64 v2, v[6:7], v[18:19] offset1:34
	ds_write2_b64 v3, v[14:15], v[20:21] offset0:16 offset1:50
	ds_write2_b64 v2, v[26:27], v[30:31] offset0:136 offset1:170
	ds_write2_b64 v3, v[24:25], v[8:9] offset0:152 offset1:186
	ds_write2_b64 v2, v[28:29], v[10:11] offset0:68 offset1:102
	ds_write2_b64 v3, v[22:23], v[4:5] offset0:84 offset1:118
	ds_write2_b64 v2, v[58:59], v[12:13] offset0:204 offset1:238
	ds_write2_b64 v3, v[16:17], v[0:1] offset0:220 offset1:254
	s_waitcnt lgkmcnt(0)
	s_barrier
	s_add_u32 s100, s38, 0x800000
	s_addc_u32 s101, s39, 0
	v_lshl_add_u64 v[224:225], v[48:49], 1, s[100:101]
	global_load_dword v226, v[224:225], off
	s_add_u32 s100, s38, 0x1400000
	s_addc_u32 s101, s39, 0
	v_lshl_add_u64 v[228:229], v[48:49], 1, s[100:101]
	global_load_dword v226, v[228:229], off
	s_nop 0
	v_and_b32_e32 v98, 0x1ff, v41
	v_cvt_f32_u32_e32 v24, v98
	v_ashrrev_i32_e32 v0, 4, v41
	v_lshlrev_b32_e32 v0, 3, v0
	v_lshlrev_b32_e32 v1, 3, v41
	v_mul_f32_e32 v60, 0x39000000, v24
	v_sin_f32_e32 v24, v60
	v_cos_f32_e32 v60, v60
	v_add3_u32 v25, 0, v0, v1
	ds_read_b64 v[0:1], v25
	ds_read_b64 v[2:3], v25 offset:4352
	ds_read_b64 v[4:5], v25 offset:8704
	ds_read_b64 v[6:7], v25 offset:13056
	ds_read_b64 v[8:9], v25 offset:17408
	ds_read_b64 v[10:11], v25 offset:21760
	ds_read_b64 v[12:13], v25 offset:26112
	ds_read_b64 v[14:15], v25 offset:30464
	v_xor_b32_e32 v61, 0x80000000, v24
	s_waitcnt lgkmcnt(6)
	v_pk_mul_f32 v[94:95], v[2:3], v[24:25] op_sel:[1,0] op_sel_hi:[0,0] neg_hi:[0,1]
	v_pk_fma_f32 v[2:3], v[2:3], v[60:61], v[94:95] op_sel_hi:[1,0,1]
	v_pk_mul_f32 v[94:95], v[24:25], v[60:61] op_sel:[0,1] op_sel_hi:[0,0] neg_hi:[1,0]
	v_pk_fma_f32 v[94:95], v[60:61], v[60:61], v[94:95] op_sel_hi:[0,1,1]
	ds_read_b64 v[16:17], v25 offset:34816
	ds_read_b64 v[18:19], v25 offset:39168
	ds_read_b64 v[20:21], v25 offset:43520
	ds_read_b64 v[22:23], v25 offset:47872
	s_waitcnt lgkmcnt(9)
	v_pk_mul_f32 v[96:97], v[4:5], v[94:95] op_sel:[1,1] op_sel_hi:[0,1] neg_lo:[0,1]
	v_pk_fma_f32 v[4:5], v[4:5], v[94:95], v[96:97] op_sel_hi:[1,0,1]
	v_pk_mul_f32 v[96:97], v[24:25], v[94:95] op_sel:[0,1] op_sel_hi:[0,0] neg_hi:[1,0]
	v_pk_fma_f32 v[94:95], v[60:61], v[94:95], v[96:97] op_sel_hi:[0,1,1]
	ds_read_b64 v[26:27], v25 offset:52224
	ds_read_b64 v[28:29], v25 offset:56576
	ds_read_b64 v[30:31], v25 offset:60928
	ds_read_b64 v[58:59], v25 offset:65280
	s_waitcnt lgkmcnt(12)
	v_pk_mul_f32 v[96:97], v[6:7], v[94:95] op_sel:[1,1] op_sel_hi:[0,1] neg_lo:[0,1]
	v_pk_fma_f32 v[6:7], v[6:7], v[94:95], v[96:97] op_sel_hi:[1,0,1]
	v_pk_mul_f32 v[96:97], v[24:25], v[94:95] op_sel:[0,1] op_sel_hi:[0,0] neg_hi:[1,0]
	v_pk_fma_f32 v[94:95], v[60:61], v[94:95], v[96:97] op_sel_hi:[0,1,1]
	s_waitcnt lgkmcnt(0)
	v_pk_mul_f32 v[96:97], v[8:9], v[94:95] op_sel:[1,1] op_sel_hi:[0,1] neg_lo:[0,1]
	v_pk_fma_f32 v[8:9], v[8:9], v[94:95], v[96:97] op_sel_hi:[1,0,1]
	v_pk_mul_f32 v[96:97], v[24:25], v[94:95] op_sel:[0,1] op_sel_hi:[0,0] neg_hi:[1,0]
	v_pk_fma_f32 v[94:95], v[60:61], v[94:95], v[96:97] op_sel_hi:[0,1,1]
	s_barrier
	v_pk_mul_f32 v[96:97], v[10:11], v[94:95] op_sel:[1,1] op_sel_hi:[0,1] neg_lo:[0,1]
	v_pk_fma_f32 v[10:11], v[10:11], v[94:95], v[96:97] op_sel_hi:[1,0,1]
	v_pk_mul_f32 v[96:97], v[24:25], v[94:95] op_sel:[0,1] op_sel_hi:[0,0] neg_hi:[1,0]
	v_pk_fma_f32 v[94:95], v[60:61], v[94:95], v[96:97] op_sel_hi:[0,1,1]
	s_nop 0
	v_pk_mul_f32 v[96:97], v[12:13], v[94:95] op_sel:[1,1] op_sel_hi:[0,1] neg_lo:[0,1]
	v_pk_fma_f32 v[12:13], v[12:13], v[94:95], v[96:97] op_sel_hi:[1,0,1]
	v_pk_mul_f32 v[96:97], v[24:25], v[94:95] op_sel:[0,1] op_sel_hi:[0,0] neg_hi:[1,0]
	v_pk_fma_f32 v[94:95], v[60:61], v[94:95], v[96:97] op_sel_hi:[0,1,1]
	s_nop 0
	v_pk_mul_f32 v[96:97], v[14:15], v[94:95] op_sel:[1,1] op_sel_hi:[0,1] neg_lo:[0,1]
	v_pk_fma_f32 v[14:15], v[14:15], v[94:95], v[96:97] op_sel_hi:[1,0,1]
	v_pk_mul_f32 v[96:97], v[24:25], v[94:95] op_sel:[0,1] op_sel_hi:[0,0] neg_hi:[1,0]
	v_pk_fma_f32 v[94:95], v[60:61], v[94:95], v[96:97] op_sel_hi:[0,1,1]
	s_nop 0
	v_pk_mul_f32 v[96:97], v[16:17], v[94:95] op_sel:[1,1] op_sel_hi:[0,1] neg_lo:[0,1]
	v_pk_fma_f32 v[16:17], v[16:17], v[94:95], v[96:97] op_sel_hi:[1,0,1]
	v_pk_mul_f32 v[96:97], v[24:25], v[94:95] op_sel:[0,1] op_sel_hi:[0,0] neg_hi:[1,0]
	v_pk_fma_f32 v[94:95], v[60:61], v[94:95], v[96:97] op_sel_hi:[0,1,1]
	s_nop 0
	v_pk_mul_f32 v[96:97], v[18:19], v[94:95] op_sel:[1,1] op_sel_hi:[0,1] neg_lo:[0,1]
	v_pk_fma_f32 v[18:19], v[18:19], v[94:95], v[96:97] op_sel_hi:[1,0,1]
	v_pk_mul_f32 v[96:97], v[24:25], v[94:95] op_sel:[0,1] op_sel_hi:[0,0] neg_hi:[1,0]
	v_pk_fma_f32 v[94:95], v[60:61], v[94:95], v[96:97] op_sel_hi:[0,1,1]
	s_nop 0
	v_pk_mul_f32 v[96:97], v[20:21], v[94:95] op_sel:[1,1] op_sel_hi:[0,1] neg_lo:[0,1]
	v_pk_fma_f32 v[20:21], v[20:21], v[94:95], v[96:97] op_sel_hi:[1,0,1]
	v_pk_mul_f32 v[96:97], v[24:25], v[94:95] op_sel:[0,1] op_sel_hi:[0,0] neg_hi:[1,0]
	v_pk_fma_f32 v[94:95], v[60:61], v[94:95], v[96:97] op_sel_hi:[0,1,1]
	s_nop 0
	v_pk_mul_f32 v[96:97], v[22:23], v[94:95] op_sel:[1,1] op_sel_hi:[0,1] neg_lo:[0,1]
	v_pk_fma_f32 v[22:23], v[22:23], v[94:95], v[96:97] op_sel_hi:[1,0,1]
	v_pk_mul_f32 v[96:97], v[24:25], v[94:95] op_sel:[0,1] op_sel_hi:[0,0] neg_hi:[1,0]
	v_pk_fma_f32 v[94:95], v[60:61], v[94:95], v[96:97] op_sel_hi:[0,1,1]
	s_nop 0
	v_pk_mul_f32 v[96:97], v[26:27], v[94:95] op_sel:[1,1] op_sel_hi:[0,1] neg_lo:[0,1]
	v_pk_fma_f32 v[26:27], v[26:27], v[94:95], v[96:97] op_sel_hi:[1,0,1]
	v_pk_mul_f32 v[96:97], v[24:25], v[94:95] op_sel:[0,1] op_sel_hi:[0,0] neg_hi:[1,0]
	v_pk_fma_f32 v[94:95], v[60:61], v[94:95], v[96:97] op_sel_hi:[0,1,1]
	s_nop 0
	v_pk_mul_f32 v[96:97], v[28:29], v[94:95] op_sel:[1,1] op_sel_hi:[0,1] neg_lo:[0,1]
	v_pk_fma_f32 v[28:29], v[28:29], v[94:95], v[96:97] op_sel_hi:[1,0,1]
	v_pk_mul_f32 v[96:97], v[24:25], v[94:95] op_sel:[0,1] op_sel_hi:[0,0] neg_hi:[1,0]
	v_pk_fma_f32 v[94:95], v[60:61], v[94:95], v[96:97] op_sel_hi:[0,1,1]
	v_pk_mul_f32 v[24:25], v[24:25], v[94:95] op_sel:[0,1] op_sel_hi:[0,0] neg_hi:[1,0]
	v_pk_fma_f32 v[24:25], v[60:61], v[94:95], v[24:25] op_sel_hi:[0,1,1]
	v_pk_mul_f32 v[60:61], v[58:59], v[24:25] op_sel:[1,1] op_sel_hi:[0,1] neg_lo:[0,1]
	v_pk_fma_f32 v[24:25], v[58:59], v[24:25], v[60:61] op_sel_hi:[1,0,1]
	v_pk_add_f32 v[58:59], v[0:1], v[16:17]
	v_pk_add_f32 v[0:1], v[0:1], v[16:17] neg_lo:[0,1] neg_hi:[0,1]
	v_pk_add_f32 v[16:17], v[2:3], v[18:19]
	v_pk_add_f32 v[2:3], v[2:3], v[18:19] neg_lo:[0,1] neg_hi:[0,1]
	v_pk_mul_f32 v[96:97], v[30:31], v[94:95] op_sel:[1,1] op_sel_hi:[0,1] neg_lo:[0,1]
	v_pk_mul_f32 v[18:19], v[2:3], s[18:19]
	v_pk_fma_f32 v[30:31], v[30:31], v[94:95], v[96:97] op_sel_hi:[1,0,1]
	v_pk_fma_f32 v[2:3], v[2:3], s[30:31], v[18:19] op_sel:[0,0,1] op_sel_hi:[1,0,0]
	v_pk_add_f32 v[18:19], v[4:5], v[20:21]
	v_pk_add_f32 v[4:5], v[4:5], v[20:21] neg_lo:[0,1] neg_hi:[0,1]
	s_nop 0
	v_pk_mul_f32 v[20:21], v[4:5], s[10:11]
	s_nop 0
	v_pk_fma_f32 v[4:5], v[4:5], s[14:15], v[20:21] op_sel:[0,0,1] op_sel_hi:[1,0,0]
	v_pk_add_f32 v[20:21], v[6:7], v[22:23]
	v_pk_add_f32 v[6:7], v[6:7], v[22:23] neg_lo:[0,1] neg_hi:[0,1]
	s_nop 0
	v_pk_mul_f32 v[22:23], v[6:7], s[34:35]
	s_nop 0
	v_pk_fma_f32 v[6:7], v[6:7], s[26:27], v[22:23] op_sel:[0,0,1] op_sel_hi:[1,0,0]
	v_pk_add_f32 v[22:23], v[8:9], v[26:27]
	v_pk_add_f32 v[8:9], v[8:9], v[26:27] neg_lo:[0,1] neg_hi:[0,1]
	v_pk_add_f32 v[26:27], v[10:11], v[28:29]
	v_pk_add_f32 v[10:11], v[10:11], v[28:29] neg_lo:[0,1] neg_hi:[0,1]
	s_nop 0
	v_pk_mul_f32 v[28:29], v[10:11], s[34:35]
	s_nop 0
	v_pk_fma_f32 v[10:11], v[10:11], s[26:27], v[28:29] op_sel:[0,0,1] op_sel_hi:[1,0,0] neg_lo:[1,0,0] neg_hi:[1,0,0]
	v_pk_add_f32 v[28:29], v[12:13], v[30:31]
	v_pk_add_f32 v[12:13], v[12:13], v[30:31] neg_lo:[0,1] neg_hi:[0,1]
	s_nop 0
	v_pk_mul_f32 v[30:31], v[12:13], s[10:11]
	s_nop 0
	v_pk_fma_f32 v[12:13], v[12:13], s[14:15], v[30:31] op_sel:[0,0,1] op_sel_hi:[1,0,0] neg_lo:[1,0,0] neg_hi:[1,0,0]
	v_pk_add_f32 v[30:31], v[14:15], v[24:25]
	v_pk_add_f32 v[14:15], v[14:15], v[24:25] neg_lo:[0,1] neg_hi:[0,1]
	s_nop 0
	v_pk_mul_f32 v[24:25], v[14:15], s[18:19]
	s_nop 0
	v_pk_fma_f32 v[14:15], v[14:15], s[30:31], v[24:25] op_sel:[0,0,1] op_sel_hi:[1,0,0] neg_lo:[1,0,0] neg_hi:[1,0,0]
	v_pk_add_f32 v[24:25], v[58:59], v[22:23]
	v_pk_add_f32 v[22:23], v[58:59], v[22:23] neg_lo:[0,1] neg_hi:[0,1]
	v_pk_add_f32 v[58:59], v[16:17], v[26:27]
	v_pk_add_f32 v[16:17], v[16:17], v[26:27] neg_lo:[0,1] neg_hi:[0,1]
	s_nop 0
	v_pk_mul_f32 v[26:27], v[16:17], s[10:11]
	s_nop 0
	v_pk_fma_f32 v[16:17], v[16:17], s[14:15], v[26:27] op_sel:[0,0,1] op_sel_hi:[1,0,0]
	v_pk_add_f32 v[26:27], v[18:19], v[28:29]
	v_pk_add_f32 v[18:19], v[18:19], v[28:29] neg_lo:[0,1] neg_hi:[0,1]
	v_pk_add_f32 v[28:29], v[20:21], v[30:31]
	v_pk_add_f32 v[20:21], v[20:21], v[30:31] neg_lo:[0,1] neg_hi:[0,1]
	s_nop 0
	v_pk_mul_f32 v[30:31], v[20:21], s[10:11]
	s_nop 0
	v_pk_fma_f32 v[20:21], v[20:21], s[14:15], v[30:31] op_sel:[0,0,1] op_sel_hi:[1,0,0] neg_lo:[1,0,0] neg_hi:[1,0,0]
	v_pk_add_f32 v[30:31], v[0:1], v[8:9] op_sel:[0,1] op_sel_hi:[1,0] neg_hi:[0,1]
	v_pk_add_f32 v[0:1], v[0:1], v[8:9] op_sel:[0,1] op_sel_hi:[1,0] neg_lo:[0,1]
	v_pk_add_f32 v[8:9], v[2:3], v[10:11]
	v_pk_add_f32 v[2:3], v[2:3], v[10:11] neg_lo:[0,1] neg_hi:[0,1]
	s_nop 0
	v_pk_mul_f32 v[10:11], v[2:3], s[10:11]
	s_nop 0
	v_pk_fma_f32 v[2:3], v[2:3], s[14:15], v[10:11] op_sel:[0,0,1] op_sel_hi:[1,0,0]
	v_pk_add_f32 v[10:11], v[4:5], v[12:13]
	v_pk_add_f32 v[4:5], v[4:5], v[12:13] neg_lo:[0,1] neg_hi:[0,1]
	v_pk_add_f32 v[12:13], v[6:7], v[14:15]
	v_pk_add_f32 v[6:7], v[6:7], v[14:15] neg_lo:[0,1] neg_hi:[0,1]
	s_nop 0
	v_pk_mul_f32 v[14:15], v[6:7], s[10:11]
	s_nop 0
	v_pk_fma_f32 v[6:7], v[6:7], s[14:15], v[14:15] op_sel:[0,0,1] op_sel_hi:[1,0,0] neg_lo:[1,0,0] neg_hi:[1,0,0]
	v_pk_add_f32 v[14:15], v[24:25], v[26:27]
	v_pk_add_f32 v[24:25], v[24:25], v[26:27] neg_lo:[0,1] neg_hi:[0,1]
	v_pk_add_f32 v[26:27], v[58:59], v[28:29]
	v_pk_add_f32 v[28:29], v[58:59], v[28:29] neg_lo:[0,1] neg_hi:[0,1]
	v_pk_add_f32 v[58:59], v[22:23], v[18:19] op_sel:[0,1] op_sel_hi:[1,0] neg_hi:[0,1]
	v_pk_add_f32 v[18:19], v[22:23], v[18:19] op_sel:[0,1] op_sel_hi:[1,0] neg_lo:[0,1]
	v_pk_add_f32 v[22:23], v[16:17], v[20:21]
	v_pk_add_f32 v[16:17], v[16:17], v[20:21] neg_lo:[0,1] neg_hi:[0,1]
	v_pk_add_f32 v[20:21], v[30:31], v[10:11]
	v_pk_add_f32 v[10:11], v[30:31], v[10:11] neg_lo:[0,1] neg_hi:[0,1]
	v_pk_add_f32 v[30:31], v[8:9], v[12:13]
	v_pk_add_f32 v[8:9], v[8:9], v[12:13] neg_lo:[0,1] neg_hi:[0,1]
	v_pk_add_f32 v[12:13], v[0:1], v[4:5] op_sel:[0,1] op_sel_hi:[1,0] neg_hi:[0,1]
	v_pk_add_f32 v[0:1], v[0:1], v[4:5] op_sel:[0,1] op_sel_hi:[1,0] neg_lo:[0,1]
	v_pk_add_f32 v[4:5], v[2:3], v[6:7]
	v_pk_add_f32 v[2:3], v[2:3], v[6:7] neg_lo:[0,1] neg_hi:[0,1]
	s_nop 0
	v_pk_mul_f32 v[2:3], v[2:3], s[22:23]
	v_pk_add_f32 v[6:7], v[14:15], v[26:27]
	v_pk_add_f32 v[14:15], v[14:15], v[26:27] neg_lo:[0,1] neg_hi:[0,1]
	v_pk_add_f32 v[26:27], v[24:25], v[28:29] op_sel:[0,1] op_sel_hi:[1,0] neg_hi:[0,1]
	v_pk_add_f32 v[24:25], v[24:25], v[28:29] op_sel:[0,1] op_sel_hi:[1,0] neg_lo:[0,1]
	v_pk_add_f32 v[28:29], v[58:59], v[22:23]
	v_pk_add_f32 v[22:23], v[58:59], v[22:23] neg_lo:[0,1] neg_hi:[0,1]
	v_pk_add_f32 v[58:59], v[18:19], v[16:17] op_sel:[0,1] op_sel_hi:[1,0] neg_hi:[0,1]
	v_pk_add_f32 v[16:17], v[18:19], v[16:17] op_sel:[0,1] op_sel_hi:[1,0] neg_lo:[0,1]
	v_pk_add_f32 v[18:19], v[20:21], v[30:31]
	v_pk_add_f32 v[20:21], v[20:21], v[30:31] neg_lo:[0,1] neg_hi:[0,1]
	v_pk_add_f32 v[30:31], v[10:11], v[8:9] op_sel:[0,1] op_sel_hi:[1,0] neg_hi:[0,1]
	v_pk_add_f32 v[8:9], v[10:11], v[8:9] op_sel:[0,1] op_sel_hi:[1,0] neg_lo:[0,1]
	v_pk_add_f32 v[10:11], v[12:13], v[4:5]
	v_pk_add_f32 v[4:5], v[12:13], v[4:5] neg_lo:[0,1] neg_hi:[0,1]
	v_pk_add_f32 v[12:13], v[0:1], v[2:3] op_sel:[0,1] op_sel_hi:[1,0]
	v_pk_add_f32 v[0:1], v[0:1], v[2:3] op_sel:[0,1] op_sel_hi:[1,0] neg_lo:[0,1] neg_hi:[0,1]
	v_lshlrev_b32_e32 v2, 4, v41
	v_and_or_b32 v2, v2, s15, v98
	v_ashrrev_i32_e32 v3, 4, v2
	v_lshlrev_b32_e32 v3, 3, v3
	v_lshlrev_b32_e32 v2, 3, v2
	v_add3_u32 v2, 0, v3, v2
	ds_write_b64 v2, v[6:7]
	ds_write_b64 v2, v[14:15] offset:34816
	ds_write_b64 v2, v[26:27] offset:17408
	ds_write_b64 v2, v[24:25] offset:52224
	ds_write_b64 v2, v[28:29] offset:8704
	ds_write_b64 v2, v[22:23] offset:43520
	ds_write_b64 v2, v[58:59] offset:26112
	ds_write_b64 v2, v[16:17] offset:60928
	ds_write_b64 v2, v[18:19] offset:4352
	ds_write_b64 v2, v[20:21] offset:39168
	ds_write_b64 v2, v[30:31] offset:21760
	ds_write_b64 v2, v[8:9] offset:56576
	ds_write_b64 v2, v[10:11] offset:13056
	ds_write_b64 v2, v[4:5] offset:47872
	ds_write_b64 v2, v[12:13] offset:30464
	ds_write_b64 v2, v[0:1] offset:65280
	s_waitcnt lgkmcnt(0)
	s_barrier
	s_and_saveexec_b64 s[28:29], s[40:41]
	s_cbranch_execz .LBB0_602
	s_add_u32 s4, s38, 0x800000
	s_addc_u32 s5, s39, 0
	v_lshl_add_u64 v[0:1], v[48:49], 1, s[4:5]
	global_load_dwordx4 v[8:11], v[0:1], off offset:16
	global_load_dwordx4 v[12:15], v[0:1], off
	v_mov_b32_e32 v19, 0
	v_mov_b32_e32 v21, 0
	v_mov_b32_e32 v157, 0
	s_and_saveexec_b64 s[8:9], s[42:43]
	s_cbranch_execz .LBB0_678
	v_lshl_add_u64 v[2:3], v[172:173], 1, s[4:5]
	global_load_ushort v157, v[2:3], off offset:-2
